# sample attention: batch the five f32 cache staging loads per tile (one wait instead of five); GU2/w_in epilogue rss loads hoisted
# speedup vs baseline: 1.0009x; 1.0009x over previous
; DI unsigned pk2(float lo, float hi) { f32x2 v = {lo, hi}; bf16x2_t b = __builtin_convertvector(v, bf16x2_t); return __builtin_bit_cast(unsigned, b); }
;     DI void operator()(const f32x4 (&acc)[2][2][4][2], const pg8::Unit& u, int wr, int wc, int fr, int fq) const {
; #pragma unroll
;         for (int ai = 0; ai < 2; ++ai)
; #pragma unroll
;             for (int m = 0; m < 4; ++m) { const int r = u.pm * 256 + ai * 128 + wr * 64 + m * 16 + fr; bf16_t* rowp = O + (size_t)r * ldc + u.pn * 256 + wc * 32 + 8 * fq; const float sr = rss ? sc * rsqrtf(rss[r] * (1.f / D) + 1e-6f) : sc;
; #pragma unroll
;                 for (int bj = 0; bj < 2; ++bj) { const f32x4 a = acc[ai][bj][m][0] * sr, b = acc[ai][bj][m][1] * sr; u32x4 w; w.x = pk2(a[0], a[1]); w.y = pk2(a[2], a[3]); w.z = pk2(b[0], b[1]); w.w = pk2(b[2], b[3]); *(u32x4*)(rowp + bj * 128) = w; } }
;     }
.LBB0_909:
	v_lshl_add_u32 v172, s18, 8, v150
	v_add_u32_e32 v200, 0xb0, v172
	v_ashrrev_i32_e32 v201, 31, v200
	v_lshl_add_u64 v[198:199], v[200:201], 2, s[8:9]
	v_add_u32_e32 v196, 0xa0, v172
	v_ashrrev_i32_e32 v197, 31, v196
	v_lshl_add_u64 v[194:195], v[196:197], 2, s[8:9]
	v_add_u32_e32 v192, 0x90, v172
	v_ashrrev_i32_e32 v193, 31, v192
	v_lshl_add_u64 v[190:191], v[192:193], 2, s[8:9]
	v_add_u32_e32 v188, 0x80, v172
	v_ashrrev_i32_e32 v189, 31, v188
	v_lshl_add_u64 v[186:187], v[188:189], 2, s[8:9]
	v_or_b32_e32 v184, 48, v172
	v_ashrrev_i32_e32 v185, 31, v184
	v_lshl_add_u64 v[182:183], v[184:185], 2, s[8:9]
	v_or_b32_e32 v180, 32, v172
	v_ashrrev_i32_e32 v181, 31, v180
	v_lshl_add_u64 v[178:179], v[180:181], 2, s[8:9]
	v_or_b32_e32 v176, 16, v172
	v_ashrrev_i32_e32 v177, 31, v176
	v_lshl_add_u64 v[174:175], v[176:177], 2, s[8:9]
	v_ashrrev_i32_e32 v173, 31, v172
	v_lshl_add_u64 v[170:171], v[172:173], 2, s[8:9]
	global_load_dword v162, v[170:171], off
	global_load_dword v163, v[174:175], off
	global_load_dword v164, v[178:179], off
	global_load_dword v165, v[182:183], off
	global_load_dword v166, v[186:187], off
	global_load_dword v167, v[190:191], off
	global_load_dword v168, v[194:195], off
	global_load_dword v169, v[198:199], off
	s_lshl_b32 s16, s19, 8
	v_readlane_b32 s18, v247, 62
	v_readlane_b32 s19, v247, 63
	s_ashr_i32 s17, s16, 31
	s_waitcnt vmcnt(7)
	v_fmamk_f32 v149, v162, 0x3a800000, v155
	v_cmp_gt_f32_e32 vcc, s55, v149
	v_mul_f32_e32 v158, 0x4b800000, v149
	v_mov_b64_e32 v[146:147], s[18:19]
	v_cndmask_b32_e32 v149, v149, v158, vcc
	v_rsq_f32_e32 v149, v149
	v_mad_i64_i32 v[156:157], s[18:19], v172, s54, v[146:147]
	s_lshl_b64 s[18:19], s[16:17], 1
	v_mul_f32_e32 v158, 0x45800000, v149
	v_lshl_add_u64 v[156:157], v[156:157], 0, s[18:19]
	v_cndmask_b32_e32 v158, v149, v158, vcc
	v_lshl_add_u64 v[156:157], v[156:157], 0, s[0:1]
	v_pk_mul_f32 v[126:127], v[126:127], v[158:159] op_sel_hi:[1,0]
	v_pk_mul_f32 v[124:125], v[124:125], v[158:159] op_sel_hi:[1,0]
	v_pk_mul_f32 v[160:161], v[122:123], v[158:159] op_sel_hi:[1,0]
	v_pk_mul_f32 v[122:123], v[120:121], v[158:159] op_sel_hi:[1,0]
	v_lshl_add_u64 v[156:157], v[156:157], 0, v[136:137]
	v_cvt_pk_bf16_f32 v120, v124, v125
	v_cvt_pk_bf16_f32 v121, v126, v127
	v_cvt_pk_bf16_f32 v122, v122, v123
	v_cvt_pk_bf16_f32 v123, v160, v161
	global_store_dwordx4 v[156:157], v[120:123], off
	v_pk_mul_f32 v[118:119], v[118:119], v[158:159] op_sel_hi:[1,0]
	v_pk_mul_f32 v[116:117], v[116:117], v[158:159] op_sel_hi:[1,0]
	v_pk_mul_f32 v[120:121], v[114:115], v[158:159] op_sel_hi:[1,0]
	v_pk_mul_f32 v[114:115], v[112:113], v[158:159] op_sel_hi:[1,0]
	v_cvt_pk_bf16_f32 v112, v116, v117
	v_cvt_pk_bf16_f32 v113, v118, v119
	v_cvt_pk_bf16_f32 v114, v114, v115
	v_cvt_pk_bf16_f32 v115, v120, v121
	global_store_dwordx4 v[156:157], v[112:115], off offset:256
	s_nop 1
	s_nop 0
	s_nop 0
	v_mad_i64_i32 v[114:115], s[16:17], v176, s54, v[146:147]
	s_nop 0
	s_nop 0
	v_lshl_add_u64 v[114:115], v[114:115], 0, s[18:19]
	v_lshl_add_u64 v[114:115], v[114:115], 0, s[0:1]
	v_lshl_add_u64 v[114:115], v[114:115], 0, v[136:137]
	s_waitcnt vmcnt(8)
	v_fmamk_f32 v112, v163, 0x3a800000, v155
	v_cmp_gt_f32_e32 vcc, s55, v112
	v_mul_f32_e32 v113, 0x4b800000, v112
	s_nop 0
	v_cndmask_b32_e32 v112, v112, v113, vcc
	v_rsq_f32_e32 v112, v112
	s_nop 0
	v_mul_f32_e32 v113, 0x45800000, v112
	v_cndmask_b32_e32 v112, v112, v113, vcc
	v_pk_mul_f32 v[110:111], v[110:111], v[112:113] op_sel_hi:[1,0]
	v_pk_mul_f32 v[108:109], v[108:109], v[112:113] op_sel_hi:[1,0]
	v_pk_mul_f32 v[116:117], v[106:107], v[112:113] op_sel_hi:[1,0]
	v_pk_mul_f32 v[106:107], v[104:105], v[112:113] op_sel_hi:[1,0]
	v_cvt_pk_bf16_f32 v104, v108, v109
	v_cvt_pk_bf16_f32 v105, v110, v111
	v_cvt_pk_bf16_f32 v106, v106, v107
	v_cvt_pk_bf16_f32 v107, v116, v117
	global_store_dwordx4 v[114:115], v[104:107], off
	v_pk_mul_f32 v[102:103], v[102:103], v[112:113] op_sel_hi:[1,0]
	v_pk_mul_f32 v[100:101], v[100:101], v[112:113] op_sel_hi:[1,0]
	v_pk_mul_f32 v[104:105], v[98:99], v[112:113] op_sel_hi:[1,0]
	v_pk_mul_f32 v[98:99], v[96:97], v[112:113] op_sel_hi:[1,0]
	v_cvt_pk_bf16_f32 v96, v100, v101
	v_cvt_pk_bf16_f32 v97, v102, v103
	v_cvt_pk_bf16_f32 v98, v98, v99
	v_cvt_pk_bf16_f32 v99, v104, v105
	global_store_dwordx4 v[114:115], v[96:99], off offset:256
	s_nop 1
	s_nop 0
	s_nop 0
	v_mad_i64_i32 v[98:99], s[16:17], v180, s54, v[146:147]
	s_nop 0
	s_nop 0
	v_lshl_add_u64 v[98:99], v[98:99], 0, s[18:19]
	v_lshl_add_u64 v[98:99], v[98:99], 0, s[0:1]
	v_lshl_add_u64 v[98:99], v[98:99], 0, v[136:137]
	s_waitcnt vmcnt(9)
	v_fmamk_f32 v96, v164, 0x3a800000, v155
	v_cmp_gt_f32_e32 vcc, s55, v96
	v_mul_f32_e32 v97, 0x4b800000, v96
	s_nop 0
	v_cndmask_b32_e32 v96, v96, v97, vcc
	v_rsq_f32_e32 v96, v96
	s_nop 0
	v_mul_f32_e32 v97, 0x45800000, v96
	v_cndmask_b32_e32 v96, v96, v97, vcc
	v_pk_mul_f32 v[94:95], v[94:95], v[96:97] op_sel_hi:[1,0]
	v_pk_mul_f32 v[92:93], v[92:93], v[96:97] op_sel_hi:[1,0]
	v_pk_mul_f32 v[100:101], v[90:91], v[96:97] op_sel_hi:[1,0]
	v_pk_mul_f32 v[90:91], v[88:89], v[96:97] op_sel_hi:[1,0]
	v_cvt_pk_bf16_f32 v88, v92, v93
	v_cvt_pk_bf16_f32 v89, v94, v95
	v_cvt_pk_bf16_f32 v90, v90, v91
	v_cvt_pk_bf16_f32 v91, v100, v101
	global_store_dwordx4 v[98:99], v[88:91], off
	v_pk_mul_f32 v[86:87], v[86:87], v[96:97] op_sel_hi:[1,0]
	v_pk_mul_f32 v[84:85], v[84:85], v[96:97] op_sel_hi:[1,0]
	v_pk_mul_f32 v[88:89], v[82:83], v[96:97] op_sel_hi:[1,0]
	v_pk_mul_f32 v[82:83], v[80:81], v[96:97] op_sel_hi:[1,0]
	v_cvt_pk_bf16_f32 v80, v84, v85
	v_cvt_pk_bf16_f32 v81, v86, v87
	v_cvt_pk_bf16_f32 v82, v82, v83
	v_cvt_pk_bf16_f32 v83, v88, v89
	global_store_dwordx4 v[98:99], v[80:83], off offset:256
	s_nop 1
	s_nop 0
	s_nop 0
	v_mad_i64_i32 v[82:83], s[16:17], v184, s54, v[146:147]
	s_nop 0
	s_nop 0
	v_lshl_add_u64 v[82:83], v[82:83], 0, s[18:19]
	v_lshl_add_u64 v[82:83], v[82:83], 0, s[0:1]
	v_lshl_add_u64 v[82:83], v[82:83], 0, v[136:137]
	s_waitcnt vmcnt(10)
; DI unsigned pk2(float lo, float hi) { f32x2 v = {lo, hi}; bf16x2_t b = __builtin_convertvector(v, bf16x2_t); return __builtin_bit_cast(unsigned, b); }
;     DI void operator()(const f32x4 (&acc)[2][2][4][2], const pg8::Unit& u, int wr, int wc, int fr, int fq) const {
; #pragma unroll
;         for (int ai = 0; ai < 2; ++ai)
; #pragma unroll
;             for (int m = 0; m < 4; ++m) { const int r = u.pm * 256 + ai * 128 + wr * 64 + m * 16 + fr; bf16_t* rowp = O + (size_t)r * ldc + u.pn * 256 + wc * 32 + 8 * fq; const float sr = rss ? sc * rsqrtf(rss[r] * (1.f / D) + 1e-6f) : sc;
; #pragma unroll
;                 for (int bj = 0; bj < 2; ++bj) { const f32x4 a = acc[ai][bj][m][0] * sr, b = acc[ai][bj][m][1] * sr; u32x4 w; w.x = pk2(a[0], a[1]); w.y = pk2(a[2], a[3]); w.z = pk2(b[0], b[1]); w.w = pk2(b[2], b[3]); *(u32x4*)(rowp + bj * 128) = w; } }
;     }
	v_fmamk_f32 v80, v165, 0x3a800000, v155
	v_cmp_gt_f32_e32 vcc, s55, v80
	v_mul_f32_e32 v81, 0x4b800000, v80
	s_nop 0
	v_cndmask_b32_e32 v80, v80, v81, vcc
	v_rsq_f32_e32 v80, v80
	s_nop 0
	v_mul_f32_e32 v81, 0x45800000, v80
	v_cndmask_b32_e32 v80, v80, v81, vcc
	v_pk_mul_f32 v[78:79], v[78:79], v[80:81] op_sel_hi:[1,0]
	v_pk_mul_f32 v[76:77], v[76:77], v[80:81] op_sel_hi:[1,0]
	v_pk_mul_f32 v[84:85], v[74:75], v[80:81] op_sel_hi:[1,0]
	v_pk_mul_f32 v[74:75], v[72:73], v[80:81] op_sel_hi:[1,0]
	v_cvt_pk_bf16_f32 v72, v76, v77
	v_cvt_pk_bf16_f32 v73, v78, v79
	v_cvt_pk_bf16_f32 v74, v74, v75
	v_cvt_pk_bf16_f32 v75, v84, v85
	global_store_dwordx4 v[82:83], v[72:75], off
	v_pk_mul_f32 v[70:71], v[70:71], v[80:81] op_sel_hi:[1,0]
	v_pk_mul_f32 v[68:69], v[68:69], v[80:81] op_sel_hi:[1,0]
	v_pk_mul_f32 v[72:73], v[66:67], v[80:81] op_sel_hi:[1,0]
	v_pk_mul_f32 v[66:67], v[64:65], v[80:81] op_sel_hi:[1,0]
	v_cvt_pk_bf16_f32 v64, v68, v69
	v_cvt_pk_bf16_f32 v65, v70, v71
	v_cvt_pk_bf16_f32 v66, v66, v67
	v_cvt_pk_bf16_f32 v67, v72, v73
	global_store_dwordx4 v[82:83], v[64:67], off offset:256
	s_nop 1
	s_nop 0
	s_nop 0
	v_mad_i64_i32 v[66:67], s[16:17], v188, s54, v[146:147]
	s_nop 0
	s_nop 0
	v_lshl_add_u64 v[66:67], v[66:67], 0, s[18:19]
	v_lshl_add_u64 v[66:67], v[66:67], 0, s[0:1]
	v_lshl_add_u64 v[66:67], v[66:67], 0, v[136:137]
	s_waitcnt vmcnt(11)
	v_fmamk_f32 v64, v166, 0x3a800000, v155
	v_cmp_gt_f32_e32 vcc, s55, v64
	v_mul_f32_e32 v65, 0x4b800000, v64
	s_nop 0
	v_cndmask_b32_e32 v64, v64, v65, vcc
	v_rsq_f32_e32 v64, v64
	s_nop 0
	v_mul_f32_e32 v65, 0x45800000, v64
	v_cndmask_b32_e32 v64, v64, v65, vcc
	v_pk_mul_f32 v[62:63], v[62:63], v[64:65] op_sel_hi:[1,0]
	v_pk_mul_f32 v[60:61], v[60:61], v[64:65] op_sel_hi:[1,0]
	v_pk_mul_f32 v[68:69], v[58:59], v[64:65] op_sel_hi:[1,0]
	v_pk_mul_f32 v[58:59], v[56:57], v[64:65] op_sel_hi:[1,0]
	v_cvt_pk_bf16_f32 v56, v60, v61
	v_cvt_pk_bf16_f32 v57, v62, v63
	v_cvt_pk_bf16_f32 v58, v58, v59
	v_cvt_pk_bf16_f32 v59, v68, v69
	global_store_dwordx4 v[66:67], v[56:59], off
	v_pk_mul_f32 v[54:55], v[54:55], v[64:65] op_sel_hi:[1,0]
	v_pk_mul_f32 v[52:53], v[52:53], v[64:65] op_sel_hi:[1,0]
	v_pk_mul_f32 v[56:57], v[50:51], v[64:65] op_sel_hi:[1,0]
	v_pk_mul_f32 v[50:51], v[48:49], v[64:65] op_sel_hi:[1,0]
	v_cvt_pk_bf16_f32 v48, v52, v53
	v_cvt_pk_bf16_f32 v49, v54, v55
	v_cvt_pk_bf16_f32 v50, v50, v51
	v_cvt_pk_bf16_f32 v51, v56, v57
	global_store_dwordx4 v[66:67], v[48:51], off offset:256
	s_nop 1
	s_nop 0
	s_nop 0
	v_mad_i64_i32 v[50:51], s[16:17], v192, s54, v[146:147]
	s_nop 0
	s_nop 0
	v_lshl_add_u64 v[50:51], v[50:51], 0, s[18:19]
	v_lshl_add_u64 v[50:51], v[50:51], 0, s[0:1]
	v_lshl_add_u64 v[50:51], v[50:51], 0, v[136:137]
	s_waitcnt vmcnt(12)
	v_fmamk_f32 v48, v167, 0x3a800000, v155
	v_cmp_gt_f32_e32 vcc, s55, v48
	v_mul_f32_e32 v49, 0x4b800000, v48
	s_nop 0
	v_cndmask_b32_e32 v48, v48, v49, vcc
	v_rsq_f32_e32 v48, v48
	s_nop 0
	v_mul_f32_e32 v49, 0x45800000, v48
	v_cndmask_b32_e32 v48, v48, v49, vcc
	v_pk_mul_f32 v[46:47], v[46:47], v[48:49] op_sel_hi:[1,0]
	v_pk_mul_f32 v[44:45], v[44:45], v[48:49] op_sel_hi:[1,0]
	v_pk_mul_f32 v[52:53], v[42:43], v[48:49] op_sel_hi:[1,0]
	v_pk_mul_f32 v[42:43], v[40:41], v[48:49] op_sel_hi:[1,0]
	v_cvt_pk_bf16_f32 v40, v44, v45
	v_cvt_pk_bf16_f32 v41, v46, v47
	v_cvt_pk_bf16_f32 v42, v42, v43
	v_cvt_pk_bf16_f32 v43, v52, v53
	global_store_dwordx4 v[50:51], v[40:43], off
	v_pk_mul_f32 v[38:39], v[38:39], v[48:49] op_sel_hi:[1,0]
	v_pk_mul_f32 v[36:37], v[36:37], v[48:49] op_sel_hi:[1,0]
	v_pk_mul_f32 v[40:41], v[34:35], v[48:49] op_sel_hi:[1,0]
	v_pk_mul_f32 v[34:35], v[32:33], v[48:49] op_sel_hi:[1,0]
	v_cvt_pk_bf16_f32 v32, v36, v37
	v_cvt_pk_bf16_f32 v33, v38, v39
	v_cvt_pk_bf16_f32 v34, v34, v35
	v_cvt_pk_bf16_f32 v35, v40, v41
	global_store_dwordx4 v[50:51], v[32:35], off offset:256
	s_nop 1
	s_nop 0
	s_nop 0
	v_mad_i64_i32 v[34:35], s[16:17], v196, s54, v[146:147]
	s_nop 0
	s_nop 0
	v_lshl_add_u64 v[34:35], v[34:35], 0, s[18:19]
	v_lshl_add_u64 v[34:35], v[34:35], 0, s[0:1]
	v_lshl_add_u64 v[34:35], v[34:35], 0, v[136:137]
	s_waitcnt vmcnt(13)
	v_fmamk_f32 v32, v168, 0x3a800000, v155
	v_cmp_gt_f32_e32 vcc, s55, v32
	v_mul_f32_e32 v33, 0x4b800000, v32
	s_nop 0
	v_cndmask_b32_e32 v32, v32, v33, vcc
	v_rsq_f32_e32 v32, v32
	s_nop 0
	v_mul_f32_e32 v33, 0x45800000, v32
	v_cndmask_b32_e32 v32, v32, v33, vcc
	v_pk_mul_f32 v[30:31], v[30:31], v[32:33] op_sel_hi:[1,0]
	v_pk_mul_f32 v[28:29], v[28:29], v[32:33] op_sel_hi:[1,0]
	v_pk_mul_f32 v[36:37], v[26:27], v[32:33] op_sel_hi:[1,0]
	v_pk_mul_f32 v[26:27], v[24:25], v[32:33] op_sel_hi:[1,0]
	v_cvt_pk_bf16_f32 v24, v28, v29
	v_cvt_pk_bf16_f32 v25, v30, v31
	v_cvt_pk_bf16_f32 v26, v26, v27
	v_cvt_pk_bf16_f32 v27, v36, v37
	global_store_dwordx4 v[34:35], v[24:27], off
	v_pk_mul_f32 v[22:23], v[22:23], v[32:33] op_sel_hi:[1,0]
	v_pk_mul_f32 v[20:21], v[20:21], v[32:33] op_sel_hi:[1,0]
	v_pk_mul_f32 v[24:25], v[18:19], v[32:33] op_sel_hi:[1,0]
	v_pk_mul_f32 v[18:19], v[16:17], v[32:33] op_sel_hi:[1,0]
	v_cvt_pk_bf16_f32 v16, v20, v21
	v_cvt_pk_bf16_f32 v17, v22, v23
	v_cvt_pk_bf16_f32 v18, v18, v19
	v_cvt_pk_bf16_f32 v19, v24, v25
	global_store_dwordx4 v[34:35], v[16:19], off offset:256
	s_nop 1
	s_nop 0
	s_nop 0
	s_nop 0
	s_nop 0
	s_waitcnt vmcnt(14)
	v_fmamk_f32 v17, v169, 0x3a800000, v155
	v_cmp_gt_f32_e32 vcc, s55, v17
	v_mul_f32_e32 v18, 0x4b800000, v17
	s_nop 0
	v_cndmask_b32_e32 v17, v17, v18, vcc
	v_rsq_f32_e32 v17, v17
	s_nop 0
	v_mul_f32_e32 v18, 0x45800000, v17
	v_cndmask_b32_e32 v18, v17, v18, vcc
	v_mad_i64_i32 v[16:17], s[16:17], v200, s54, v[146:147]
	v_lshl_add_u64 v[16:17], v[16:17], 0, s[18:19]
	v_lshl_add_u64 v[16:17], v[16:17], 0, s[0:1]
	v_pk_mul_f32 v[14:15], v[14:15], v[18:19] op_sel_hi:[1,0]
	v_pk_mul_f32 v[12:13], v[12:13], v[18:19] op_sel_hi:[1,0]
	v_pk_mul_f32 v[20:21], v[10:11], v[18:19] op_sel_hi:[1,0]
	v_pk_mul_f32 v[10:11], v[8:9], v[18:19] op_sel_hi:[1,0]
	v_lshl_add_u64 v[16:17], v[16:17], 0, v[136:137]
	v_cvt_pk_bf16_f32 v8, v12, v13
	v_cvt_pk_bf16_f32 v9, v14, v15
	v_cvt_pk_bf16_f32 v10, v10, v11
	v_cvt_pk_bf16_f32 v11, v20, v21
	global_store_dwordx4 v[16:17], v[8:11], off
	v_pk_mul_f32 v[6:7], v[6:7], v[18:19] op_sel_hi:[1,0]
	v_pk_mul_f32 v[4:5], v[4:5], v[18:19] op_sel_hi:[1,0]
	v_pk_mul_f32 v[8:9], v[2:3], v[18:19] op_sel_hi:[1,0]
	v_pk_mul_f32 v[2:3], v[0:1], v[18:19] op_sel_hi:[1,0]
	v_cvt_pk_bf16_f32 v0, v4, v5
	v_cvt_pk_bf16_f32 v1, v6, v7
	v_cvt_pk_bf16_f32 v2, v2, v3
	v_cvt_pk_bf16_f32 v3, v8, v9
	s_mov_b64 s[18:19], -1
	s_andn2_b64 vcc, exec, s[4:5]
	global_store_dwordx4 v[16:17], v[0:3], off offset:256
	s_cbranch_vccnz .LBB0_898
	s_andn2_b64 vcc, exec, s[6:7]
	s_cbranch_vccnz .LBB0_897
	s_barrier
	s_branch .LBB0_897

; DI unsigned pk2(float lo, float hi) { f32x2 v = {lo, hi}; bf16x2_t b = __builtin_convertvector(v, bf16x2_t); return __builtin_bit_cast(unsigned, b); }
;     ...
;     if (SAMPLE) {
;         bf16_t* Kt = (bf16_t*)lds; bf16_t* Vt = (bf16_t*)(lds + 64 * KSTR * 2);
;         for (int t = 0; t < ntiles; ++t) {
;             __syncthreads();
;             const int rb = t == 0 ? r0 : r1 + 64 * (t - 1);
; #pragma unroll
;             for (int i = 0; i < NKC; ++i) { const int e = tid + 512 * i, row = e / CPR, cc = e % CPR; u32x4 w;
;                 if (t < 33) {
;                     if (cc < 32) { const f32x4 a = *(const f32x4*)(cckv + (size_t)(rb + row) * 256 + 8 * cc), b2 = *(const f32x4*)(cckv + (size_t)(rb + row) * 256 + 8 * cc + 4); w.x = pk2(a.x, a.y); w.y = pk2(a.z, a.w); w.z = pk2(b2.x, b2.y); w.w = pk2(b2.z, b2.w); }
;                     else { const int q8 = cc - 32; const f32x4 a = *(const f32x4*)(ckr + (size_t)(rb + row) * 64 + 4 * q8), b2 = *(const f32x4*)(ckr + (size_t)(rb + row) * 64 + 32 + 4 * q8); w.x = pk2(a.x, b2.x); w.y = pk2(a.y, b2.y); w.z = pk2(a.z, b2.z); w.w = pk2(a.w, b2.w); }
;                 } else w = cc < 32 ? *(const u32x4*)(k1 + (size_t)row * ldk1 + 8 * cc) : *(const u32x4*)(k2 + (size_t)row * ldk2 + 8 * (cc - 32));
;                 *(u32x4*)(Kt + row * KSTR + 8 * cc) = w;
;                 if (cc < 32 && (cc >> 4) == ps) { const int d0 = 8 * (cc - 16 * ps); const unsigned* wp = (const unsigned*)&w;
; #pragma unroll
;                     for (int j = 0; j < 4; ++j) { Vt[(d0 + 2 * j) * VSTR + row] = (bf16_t)(wp[j] & 0xffffu); Vt[(d0 + 2 * j + 1) * VSTR + row] = (bf16_t)(wp[j] >> 16); } }
;             }
.LBB0_1934:
	s_cmpk_eq_i32 s26, 0xffd0
	s_cselect_b64 s[16:17], -1, 0
	s_and_b64 s[0:1], s[16:17], exec
	s_cselect_b32 s27, 0, s26
	s_cmpk_lg_i32 s26, 0x810
	s_cselect_b64 s[22:23], -1, 0
	s_mov_b64 s[0:1], -1
	s_and_b64 vcc, exec, s[22:23]
	s_barrier
	s_cbranch_vccz .LBB0_1978
	s_mov_b64 s[38:39], exec
	v_add_u32_e32 v6, s27, v218
	v_ashrrev_i32_e32 v7, 31, v6
	v_lshlrev_b64 v[2:3], 8, v[6:7]
	v_lshlrev_b64 v[4:5], 10, v[6:7]
	v_lshl_add_u64 v[2:3], v[202:203], 0, v[2:3]
	v_lshl_add_u64 v[4:5], v[184:185], 0, v[4:5]
	s_and_b64 exec, s[38:39], s[6:7]
	global_load_dwordx4 v[80:83], v[2:3], off
	global_load_dwordx4 v[84:87], v[2:3], off offset:128
	s_andn2_b64 exec, s[38:39], s[6:7]
	global_load_dwordx4 v[80:83], v[4:5], off
	global_load_dwordx4 v[84:87], v[4:5], off offset:16
	s_mov_b64 exec, s[38:39]
	v_add_u32_e32 v6, s27, v222
	v_ashrrev_i32_e32 v7, 31, v6
	v_lshlrev_b64 v[2:3], 8, v[6:7]
	v_lshlrev_b64 v[4:5], 10, v[6:7]
	v_lshl_add_u64 v[2:3], v[204:205], 0, v[2:3]
	v_lshl_add_u64 v[4:5], v[186:187], 0, v[4:5]
	s_and_b64 exec, s[38:39], s[8:9]
	global_load_dwordx4 v[88:91], v[2:3], off
	global_load_dwordx4 v[92:95], v[2:3], off offset:128
	s_andn2_b64 exec, s[38:39], s[8:9]
	global_load_dwordx4 v[88:91], v[4:5], off
	global_load_dwordx4 v[92:95], v[4:5], off offset:16
	s_mov_b64 exec, s[38:39]
	v_add_u32_e32 v6, s27, v226
	v_ashrrev_i32_e32 v7, 31, v6
	v_lshlrev_b64 v[2:3], 8, v[6:7]
	v_lshlrev_b64 v[4:5], 10, v[6:7]
	v_lshl_add_u64 v[2:3], v[206:207], 0, v[2:3]
	v_lshl_add_u64 v[4:5], v[190:191], 0, v[4:5]
	s_and_b64 exec, s[38:39], s[10:11]
	global_load_dwordx4 v[96:99], v[2:3], off
	global_load_dwordx4 v[100:103], v[2:3], off offset:128
	s_andn2_b64 exec, s[38:39], s[10:11]
	global_load_dwordx4 v[96:99], v[4:5], off
	global_load_dwordx4 v[100:103], v[4:5], off offset:16
	s_mov_b64 exec, s[38:39]
	v_add_u32_e32 v6, s27, v230
	v_ashrrev_i32_e32 v7, 31, v6
	v_lshlrev_b64 v[2:3], 8, v[6:7]
	v_lshlrev_b64 v[4:5], 10, v[6:7]
	v_lshl_add_u64 v[2:3], v[208:209], 0, v[2:3]
	v_lshl_add_u64 v[4:5], v[194:195], 0, v[4:5]
	s_and_b64 exec, s[38:39], s[12:13]
	global_load_dwordx4 v[104:107], v[2:3], off
	global_load_dwordx4 v[108:111], v[2:3], off offset:128
	s_andn2_b64 exec, s[38:39], s[12:13]
	global_load_dwordx4 v[104:107], v[4:5], off
	global_load_dwordx4 v[108:111], v[4:5], off offset:16
	s_mov_b64 exec, s[38:39]
	v_add_u32_e32 v6, s27, v234
	v_ashrrev_i32_e32 v7, 31, v6
	v_lshlrev_b64 v[2:3], 8, v[6:7]
	v_lshlrev_b64 v[4:5], 10, v[6:7]
	v_lshl_add_u64 v[2:3], v[210:211], 0, v[2:3]
	v_lshl_add_u64 v[4:5], v[198:199], 0, v[4:5]
	s_and_b64 exec, s[38:39], s[14:15]
	global_load_dwordx4 v[248:251], v[2:3], off
	global_load_dwordx4 v[252:255], v[2:3], off offset:128
	s_andn2_b64 exec, s[38:39], s[14:15]
	global_load_dwordx4 v[248:251], v[4:5], off
	global_load_dwordx4 v[252:255], v[4:5], off offset:16
	s_mov_b64 exec, s[38:39]
	s_waitcnt vmcnt(0)
	s_and_b64 exec, s[38:39], s[6:7]
	v_cvt_pk_bf16_f32 v2, v80, v84
	v_cvt_pk_bf16_f32 v3, v81, v85
	v_cvt_pk_bf16_f32 v4, v82, v86
	v_cvt_pk_bf16_f32 v5, v83, v87
	s_andn2_b64 exec, s[38:39], s[6:7]
	v_cvt_pk_bf16_f32 v2, v80, v81
	v_cvt_pk_bf16_f32 v3, v82, v83
	v_cvt_pk_bf16_f32 v4, v84, v85
	v_cvt_pk_bf16_f32 v5, v86, v87
	s_mov_b64 exec, s[38:39]
	ds_write_b128 v219, v[2:5]
	s_and_b64 exec, s[38:39], s[18:19]
	ds_write_b16 v220, v2 offset:41984
	ds_write_b16_d16_hi v221, v2 offset:42120
	ds_write_b16 v220, v3 offset:42256
	ds_write_b16_d16_hi v221, v3 offset:42392
	ds_write_b16 v220, v4 offset:42528
	ds_write_b16_d16_hi v221, v4 offset:42664
	ds_write_b16 v220, v5 offset:42800
	ds_write_b16_d16_hi v221, v5 offset:42936
	s_mov_b64 exec, s[38:39]
	s_and_b64 exec, s[38:39], s[8:9]
	v_cvt_pk_bf16_f32 v2, v88, v92
	v_cvt_pk_bf16_f32 v3, v89, v93
	v_cvt_pk_bf16_f32 v4, v90, v94
	v_cvt_pk_bf16_f32 v5, v91, v95
	s_andn2_b64 exec, s[38:39], s[8:9]
	v_cvt_pk_bf16_f32 v2, v88, v89
	v_cvt_pk_bf16_f32 v3, v90, v91
	v_cvt_pk_bf16_f32 v4, v92, v93
	v_cvt_pk_bf16_f32 v5, v94, v95
	s_mov_b64 exec, s[38:39]
	ds_write_b128 v223, v[2:5]
	s_and_b64 exec, s[38:39], s[20:21]
	ds_write_b16 v224, v2 offset:41984
	ds_write_b16_d16_hi v225, v2 offset:42120
	ds_write_b16 v224, v3 offset:42256
	ds_write_b16_d16_hi v225, v3 offset:42392
	ds_write_b16 v224, v4 offset:42528
	ds_write_b16_d16_hi v225, v4 offset:42664
	ds_write_b16 v224, v5 offset:42800
	ds_write_b16_d16_hi v225, v5 offset:42936
	s_mov_b64 exec, s[38:39]
	s_and_b64 exec, s[38:39], s[10:11]
	v_cvt_pk_bf16_f32 v2, v96, v100
	v_cvt_pk_bf16_f32 v3, v97, v101
	v_cvt_pk_bf16_f32 v4, v98, v102
	v_cvt_pk_bf16_f32 v5, v99, v103
	s_andn2_b64 exec, s[38:39], s[10:11]
	v_cvt_pk_bf16_f32 v2, v96, v97
	v_cvt_pk_bf16_f32 v3, v98, v99
	v_cvt_pk_bf16_f32 v4, v100, v101
	v_cvt_pk_bf16_f32 v5, v102, v103
	s_mov_b64 exec, s[38:39]
	ds_write_b128 v227, v[2:5]
	s_and_b64 exec, s[38:39], s[68:69]
	ds_write_b16 v228, v2 offset:41984
	ds_write_b16_d16_hi v229, v2 offset:42120
	ds_write_b16 v228, v3 offset:42256
	ds_write_b16_d16_hi v229, v3 offset:42392
	ds_write_b16 v228, v4 offset:42528
	ds_write_b16_d16_hi v229, v4 offset:42664
	ds_write_b16 v228, v5 offset:42800
	ds_write_b16_d16_hi v229, v5 offset:42936
	s_mov_b64 exec, s[38:39]
	s_and_b64 exec, s[38:39], s[12:13]
	v_cvt_pk_bf16_f32 v2, v104, v108
	v_cvt_pk_bf16_f32 v3, v105, v109
	v_cvt_pk_bf16_f32 v4, v106, v110
	v_cvt_pk_bf16_f32 v5, v107, v111
	s_andn2_b64 exec, s[38:39], s[12:13]
	v_cvt_pk_bf16_f32 v2, v104, v105
	v_cvt_pk_bf16_f32 v3, v106, v107
	v_cvt_pk_bf16_f32 v4, v108, v109
	v_cvt_pk_bf16_f32 v5, v110, v111
	s_mov_b64 exec, s[38:39]
	ds_write_b128 v231, v[2:5]
	s_and_b64 exec, s[38:39], s[80:81]
	ds_write_b16 v232, v2 offset:41984
	ds_write_b16_d16_hi v233, v2 offset:42120
	ds_write_b16 v232, v3 offset:42256
	ds_write_b16_d16_hi v233, v3 offset:42392
	ds_write_b16 v232, v4 offset:42528
	ds_write_b16_d16_hi v233, v4 offset:42664
	ds_write_b16 v232, v5 offset:42800
	ds_write_b16_d16_hi v233, v5 offset:42936
	s_mov_b64 exec, s[38:39]
	s_and_b64 exec, s[38:39], s[14:15]
	v_cvt_pk_bf16_f32 v2, v248, v252
	v_cvt_pk_bf16_f32 v3, v249, v253
	v_cvt_pk_bf16_f32 v4, v250, v254
	v_cvt_pk_bf16_f32 v5, v251, v255
	s_andn2_b64 exec, s[38:39], s[14:15]
	v_cvt_pk_bf16_f32 v2, v248, v249
	v_cvt_pk_bf16_f32 v3, v250, v251
	v_cvt_pk_bf16_f32 v4, v252, v253
	v_cvt_pk_bf16_f32 v5, v254, v255
	s_mov_b64 exec, s[38:39]
	ds_write_b128 v235, v[2:5]
	s_and_b64 exec, s[38:39], s[24:25]
	ds_write_b16 v236, v2 offset:41984
	ds_write_b16_d16_hi v237, v2 offset:42120
	ds_write_b16 v236, v3 offset:42256
	ds_write_b16_d16_hi v237, v3 offset:42392
	ds_write_b16 v236, v4 offset:42528
	ds_write_b16_d16_hi v237, v4 offset:42664
	ds_write_b16 v236, v5 offset:42800
	ds_write_b16_d16_hi v237, v5 offset:42936
	s_mov_b64 exec, s[38:39]
	s_mov_b64 s[22:23], -1
	s_branch .Lsa_join
; DI unsigned pk2(float lo, float hi) { f32x2 v = {lo, hi}; bf16x2_t b = __builtin_convertvector(v, bf16x2_t); return __builtin_bit_cast(unsigned, b); }
;     ...
;             for (int i = 0; i < NKC; ++i) { const int e = tid + 512 * i, row = e / CPR, cc = e % CPR; u32x4 w;
;                 if (t < 33) {
;                     if (cc < 32) { const f32x4 a = *(const f32x4*)(cckv + (size_t)(rb + row) * 256 + 8 * cc), b2 = *(const f32x4*)(cckv + (size_t)(rb + row) * 256 + 8 * cc + 4); w.x = pk2(a.x, a.y); w.y = pk2(a.z, a.w); w.z = pk2(b2.x, b2.y); w.w = pk2(b2.z, b2.w); }
;                     else { const int q8 = cc - 32; const f32x4 a = *(const f32x4*)(ckr + (size_t)(rb + row) * 64 + 4 * q8), b2 = *(const f32x4*)(ckr + (size_t)(rb + row) * 64 + 32 + 4 * q8); w.x = pk2(a.x, b2.x); w.y = pk2(a.y, b2.y); w.z = pk2(a.z, b2.z); w.w = pk2(a.w, b2.w); }
;                 } else w = cc < 32 ? *(const u32x4*)(k1 + (size_t)row * ldk1 + 8 * cc) : *(const u32x4*)(k2 + (size_t)row * ldk2 + 8 * (cc - 32));
;                 *(u32x4*)(Kt + row * KSTR + 8 * cc) = w;
	v_add_u32_e32 v6, s27, v218
	v_ashrrev_i32_e32 v7, 31, v6
	s_and_saveexec_b64 s[0:1], s[6:7]
	s_xor_b64 s[0:1], exec, s[0:1]
	s_cbranch_execz .LBB0_1937
	v_lshlrev_b64 v[2:3], 8, v[6:7]
	v_lshl_add_u64 v[6:7], v[202:203], 0, v[2:3]
	global_load_dwordx4 v[2:5], v[6:7], off
	s_nop 0
	global_load_dwordx4 v[6:9], v[6:7], off offset:128
	s_waitcnt vmcnt(0)
	v_cvt_pk_bf16_f32 v2, v2, v6
	v_cvt_pk_bf16_f32 v3, v3, v7
	v_cvt_pk_bf16_f32 v4, v4, v8
	v_cvt_pk_bf16_f32 v5, v5, v9

; #define MFMA32(a, b, c) __builtin_amdgcn_mfma_f32_32x32x16_bf16((a), (b), (c), 0, 0, 0)
;     ...
;     auto compute = [&](const bf16_t* Kt, const bf16_t* Vt, int t) {
;         f32x16 s0, s1;
; #pragma unroll
;         for (int i = 0; i < 16; ++i) { s0[i] = 0.f; s1[i] = 0.f; }
; #pragma unroll
;         for (int ks = 0; ks < NKS; ++ks) { const bf16x8 a0 = *(const bf16x8*)(Kt + lr * KSTR + 16 * ks + 8 * hi), a1 = *(const bf16x8*)(Kt + (32 + lr) * KSTR + 16 * ks + 8 * hi);
;             bf16x8 qq;
;             if (QREG == 1) qq = qf[ks];
;             else if (QREG == 2) qq = 16 * ks < DN ? qf[ks < NQF ? ks : 0] : *(const bf16x8*)(qr_row + (16 * ks - DN) + 8 * hi);
;             else qq = 16 * ks < DN ? *(const bf16x8*)(qa_row + 16 * ks + 8 * hi) : qf[(16 * ks - DN) / 16 < NQF ? (16 * ks - DN) / 16 : 0];
;             s0 = MFMA32(a0, qq, s0); s1 = MFMA32(a1, qq, s1);
;             if ((ks & 3) == 3) __builtin_amdgcn_sched_barrier(0); }
.Lsa_join:
	s_waitcnt lgkmcnt(0)
	s_barrier
	ds_read_b128 v[2:5], v217
	s_waitcnt vmcnt(15) lgkmcnt(0)
	v_mfma_f32_32x32x16_bf16 v[80:95], v[2:5], v[112:115], 0
	ds_read_b128 v[2:5], v217 offset:20992
	s_waitcnt lgkmcnt(0)
	v_mfma_f32_32x32x16_bf16 v[96:111], v[2:5], v[112:115], 0
	ds_read_b128 v[2:5], v217 offset:32
	s_waitcnt vmcnt(14) lgkmcnt(0)
	v_mfma_f32_32x32x16_bf16 v[80:95], v[2:5], v[116:119], v[80:95]
	ds_read_b128 v[2:5], v217 offset:21024
	s_waitcnt lgkmcnt(0)
	v_mfma_f32_32x32x16_bf16 v[96:111], v[2:5], v[116:119], v[96:111]
	ds_read_b128 v[2:5], v217 offset:64
	s_waitcnt vmcnt(13) lgkmcnt(0)
	v_mfma_f32_32x32x16_bf16 v[80:95], v[2:5], v[120:123], v[80:95]
	ds_read_b128 v[2:5], v217 offset:21056
	s_waitcnt lgkmcnt(0)
	v_mfma_f32_32x32x16_bf16 v[96:111], v[2:5], v[120:123], v[96:111]
	ds_read_b128 v[2:5], v217 offset:96
	s_waitcnt vmcnt(12) lgkmcnt(0)
	v_mfma_f32_32x32x16_bf16 v[80:95], v[2:5], v[124:127], v[80:95]
	ds_read_b128 v[2:5], v217 offset:21088
	s_waitcnt lgkmcnt(0)
	v_mfma_f32_32x32x16_bf16 v[96:111], v[2:5], v[124:127], v[96:111]
	ds_read_b128 v[2:5], v217 offset:128
	s_waitcnt vmcnt(11) lgkmcnt(0)
	v_mfma_f32_32x32x16_bf16 v[80:95], v[2:5], v[128:131], v[80:95]
	ds_read_b128 v[2:5], v217 offset:21120
	s_waitcnt lgkmcnt(0)
	v_mfma_f32_32x32x16_bf16 v[96:111], v[2:5], v[128:131], v[96:111]
	ds_read_b128 v[2:5], v217 offset:160
	s_waitcnt vmcnt(10) lgkmcnt(0)
	v_mfma_f32_32x32x16_bf16 v[80:95], v[2:5], v[132:135], v[80:95]
	ds_read_b128 v[2:5], v217 offset:21152
	s_waitcnt lgkmcnt(0)
	v_mfma_f32_32x32x16_bf16 v[96:111], v[2:5], v[132:135], v[96:111]
	ds_read_b128 v[2:5], v217 offset:192
	s_waitcnt vmcnt(9) lgkmcnt(0)
	v_mfma_f32_32x32x16_bf16 v[80:95], v[2:5], v[136:139], v[80:95]
	ds_read_b128 v[2:5], v217 offset:21184
	s_waitcnt lgkmcnt(0)
	v_mfma_f32_32x32x16_bf16 v[96:111], v[2:5], v[136:139], v[96:111]
	ds_read_b128 v[2:5], v217 offset:224
	s_waitcnt vmcnt(8) lgkmcnt(0)
	v_mfma_f32_32x32x16_bf16 v[80:95], v[2:5], v[140:143], v[80:95]
	ds_read_b128 v[2:5], v217 offset:21216
	s_waitcnt lgkmcnt(0)
	v_mfma_f32_32x32x16_bf16 v[96:111], v[2:5], v[140:143], v[96:111]
	ds_read_b128 v[2:5], v217 offset:256
	s_waitcnt vmcnt(7) lgkmcnt(0)
	v_mfma_f32_32x32x16_bf16 v[80:95], v[2:5], v[144:147], v[80:95]
	ds_read_b128 v[2:5], v217 offset:21248
	s_waitcnt lgkmcnt(0)
	v_mfma_f32_32x32x16_bf16 v[96:111], v[2:5], v[144:147], v[96:111]
	ds_read_b128 v[2:5], v217 offset:288
	s_waitcnt vmcnt(6) lgkmcnt(0)
	v_mfma_f32_32x32x16_bf16 v[80:95], v[2:5], v[148:151], v[80:95]
	ds_read_b128 v[2:5], v217 offset:21280
	s_waitcnt lgkmcnt(0)
	v_mfma_f32_32x32x16_bf16 v[96:111], v[2:5], v[148:151], v[96:111]
	ds_read_b128 v[2:5], v217 offset:320
	s_waitcnt vmcnt(5) lgkmcnt(0)
	v_mfma_f32_32x32x16_bf16 v[80:95], v[2:5], v[152:155], v[80:95]
	ds_read_b128 v[2:5], v217 offset:21312
	s_waitcnt lgkmcnt(0)
	v_mfma_f32_32x32x16_bf16 v[96:111], v[2:5], v[152:155], v[96:111]
	ds_read_b128 v[2:5], v217 offset:352
	s_waitcnt vmcnt(4) lgkmcnt(0)
	v_mfma_f32_32x32x16_bf16 v[80:95], v[2:5], v[156:159], v[80:95]
	ds_read_b128 v[2:5], v217 offset:21344
	s_waitcnt lgkmcnt(0)
	v_mfma_f32_32x32x16_bf16 v[96:111], v[2:5], v[156:159], v[96:111]
	ds_read_b128 v[2:5], v217 offset:384
	s_waitcnt vmcnt(3) lgkmcnt(0)
	v_mfma_f32_32x32x16_bf16 v[80:95], v[2:5], v[160:163], v[80:95]
	ds_read_b128 v[2:5], v217 offset:21376
	s_waitcnt lgkmcnt(0)
	v_mfma_f32_32x32x16_bf16 v[96:111], v[2:5], v[160:163], v[96:111]
	ds_read_b128 v[2:5], v217 offset:416
	s_waitcnt vmcnt(2) lgkmcnt(0)
	v_mfma_f32_32x32x16_bf16 v[80:95], v[2:5], v[164:167], v[80:95]
	ds_read_b128 v[2:5], v217 offset:21408
	s_waitcnt lgkmcnt(0)
	v_mfma_f32_32x32x16_bf16 v[96:111], v[2:5], v[164:167], v[96:111]
	ds_read_b128 v[2:5], v217 offset:448
	s_waitcnt vmcnt(1) lgkmcnt(0)
	v_mfma_f32_32x32x16_bf16 v[80:95], v[2:5], v[168:171], v[80:95]
	ds_read_b128 v[2:5], v217 offset:21440
	s_waitcnt lgkmcnt(0)
	v_mfma_f32_32x32x16_bf16 v[96:111], v[2:5], v[168:171], v[96:111]
	ds_read_b128 v[2:5], v217 offset:480
	s_waitcnt vmcnt(0) lgkmcnt(0)
	v_mfma_f32_32x32x16_bf16 v[80:95], v[2:5], v[172:175], v[80:95]
	ds_read_b128 v[2:5], v217 offset:21472
	s_waitcnt lgkmcnt(0)
	v_mfma_f32_32x32x16_bf16 v[96:111], v[2:5], v[172:175], v[96:111]
	global_load_dwordx4 v[6:9], v[178:179], off offset:256
	ds_read_b128 v[2:5], v217 offset:21504
	ds_read_b128 v[10:13], v217 offset:512
	ds_read_b128 v[242:245], v217 offset:544
	s_waitcnt vmcnt(0) lgkmcnt(1)
; #define MFMA32(a, b, c) __builtin_amdgcn_mfma_f32_32x32x16_bf16((a), (b), (c), 0, 0, 0)
; DI float xhalf_max(float v) { const auto r = __builtin_amdgcn_permlane32_swap(__float_as_uint(v), __float_as_uint(v), false, false); return fmaxf(__uint_as_float(r[0]), __uint_as_float(r[1])); }
;     ...
;         for (int ks = 0; ks < NKS; ++ks) { const bf16x8 a0 = *(const bf16x8*)(Kt + lr * KSTR + 16 * ks + 8 * hi), a1 = *(const bf16x8*)(Kt + (32 + lr) * KSTR + 16 * ks + 8 * hi);
;             bf16x8 qq;
;             if (QREG == 1) qq = qf[ks];
;             else if (QREG == 2) qq = 16 * ks < DN ? qf[ks < NQF ? ks : 0] : *(const bf16x8*)(qr_row + (16 * ks - DN) + 8 * hi);
;             else qq = 16 * ks < DN ? *(const bf16x8*)(qa_row + 16 * ks + 8 * hi) : qf[(16 * ks - DN) / 16 < NQF ? (16 * ks - DN) / 16 : 0];
;             s0 = MFMA32(a0, qq, s0); s1 = MFMA32(a1, qq, s1);
;             if ((ks & 3) == 3) __builtin_amdgcn_sched_barrier(0); }
;         if (t == 0) {
; #pragma unroll
;             for (int i = 0; i < 16; ++i) { if (i >= 8) s0[i] = -INFINITY; s1[i] = -INFINITY; } }
;         float mx = s0[0];
; #pragma unroll
;         for (int i = 1; i < 16; ++i) mx = fmaxf(mx, s0[i]);
; #pragma unroll
;         for (int i = 0; i < 16; ++i) mx = fmaxf(mx, s1[i]);
;         mx = xhalf_max(mx);
;         const float mnew = fmaxf(mrun, mx), alpha = __builtin_amdgcn_exp2f(mrun - mnew);
;         const bool resc = __builtin_amdgcn_ballot_w64(mnew != mrun) != 0ull; mrun = mnew;
;         float ps = 0.f;
; #pragma unroll
;         for (int i = 0; i < 16; ++i) { s0[i] = __builtin_amdgcn_exp2f(s0[i] - mnew); s1[i] = __builtin_amdgcn_exp2f(s1[i] - mnew); ps += s0[i] + s1[i]; }
;         lrun = lrun * alpha + ps;
;         if (resc) {
; #pragma unroll
;             for (int d = 0; d < 4; ++d)
; #pragma unroll
;                 for (int i = 0; i < 16; ++i) oacc[d][i] *= alpha; }
	v_mfma_f32_32x32x16_bf16 v[80:95], v[10:13], v[6:9], v[80:95]
	v_mfma_f32_32x32x16_bf16 v[96:111], v[2:5], v[6:9], v[96:111]
	global_load_dwordx4 v[6:9], v[178:179], off offset:288
	ds_read_b128 v[2:5], v217 offset:21536
	s_waitcnt vmcnt(0) lgkmcnt(1)
	v_mfma_f32_32x32x16_bf16 v[80:95], v[242:245], v[6:9], v[80:95]
	s_waitcnt lgkmcnt(0)
	v_mfma_f32_32x32x16_bf16 v[96:111], v[2:5], v[6:9], v[96:111]
	ds_read_b128 v[2:5], v217 offset:576
	ds_read_b128 v[6:9], v217 offset:21568
	global_load_dwordx4 v[10:13], v[178:179], off offset:320
	s_waitcnt vmcnt(0) lgkmcnt(1)
	v_mfma_f32_32x32x16_bf16 v[80:95], v[2:5], v[10:13], v[80:95]
	s_waitcnt lgkmcnt(0)
	v_mfma_f32_32x32x16_bf16 v[96:111], v[6:9], v[10:13], v[96:111]
	ds_read_b128 v[2:5], v217 offset:608
	ds_read_b128 v[6:9], v217 offset:21600
	global_load_dwordx4 v[10:13], v[178:179], off offset:352
	s_waitcnt vmcnt(0) lgkmcnt(1)
	v_mfma_f32_32x32x16_bf16 v[80:95], v[2:5], v[10:13], v[80:95]
	s_waitcnt lgkmcnt(0)
	v_mfma_f32_32x32x16_bf16 v[96:111], v[6:9], v[10:13], v[96:111]
	s_nop 9
	v_max_f32_e32 v0, v81, v81
	v_max_f32_e32 v2, v80, v80
	v_max_f32_e32 v0, v2, v0
	v_max3_f32 v0, v0, v82, v83
	v_max3_f32 v0, v0, v84, v85
	v_cndmask_b32_e64 v88, v88, v215, s[16:17]
	v_cndmask_b32_e64 v15, v89, v215, s[16:17]
	v_max3_f32 v0, v0, v86, v87
	v_cndmask_b32_e64 v12, v90, v215, s[16:17]
	v_cndmask_b32_e64 v11, v91, v215, s[16:17]
	v_max3_f32 v0, v0, v88, v15
	v_cndmask_b32_e64 v8, v92, v215, s[16:17]
	v_cndmask_b32_e64 v7, v93, v215, s[16:17]
	v_max3_f32 v0, v0, v12, v11
	v_cndmask_b32_e64 v5, v94, v215, s[16:17]
	v_cndmask_b32_e64 v4, v95, v215, s[16:17]
	v_max3_f32 v0, v0, v8, v7
	v_cndmask_b32_e64 v95, v99, v215, s[16:17]
	v_cndmask_b32_e64 v99, v96, v215, s[16:17]
	v_cndmask_b32_e64 v96, v97, v215, s[16:17]
	v_max3_f32 v0, v0, v5, v4
	v_cndmask_b32_e64 v98, v98, v215, s[16:17]
	v_max3_f32 v0, v0, v99, v96
	v_cndmask_b32_e64 v94, v100, v215, s[16:17]
	v_cndmask_b32_e64 v93, v101, v215, s[16:17]
	v_max3_f32 v0, v0, v98, v95
	v_cndmask_b32_e64 v92, v102, v215, s[16:17]
	v_cndmask_b32_e64 v91, v103, v215, s[16:17]
	v_max3_f32 v0, v0, v94, v93
	v_cndmask_b32_e64 v90, v104, v215, s[16:17]
	v_cndmask_b32_e64 v89, v105, v215, s[16:17]
	v_max3_f32 v0, v0, v92, v91
	v_cndmask_b32_e64 v14, v106, v215, s[16:17]
	v_cndmask_b32_e64 v13, v107, v215, s[16:17]
	v_max3_f32 v0, v0, v90, v89
	v_cndmask_b32_e64 v10, v108, v215, s[16:17]
	v_cndmask_b32_e64 v9, v109, v215, s[16:17]
	v_max3_f32 v0, v0, v14, v13
	v_cndmask_b32_e64 v6, v110, v215, s[16:17]
	v_cndmask_b32_e64 v3, v111, v215, s[16:17]
	v_max3_f32 v0, v0, v10, v9
	v_max3_f32 v0, v0, v6, v3
	v_mov_b32_e32 v2, v0
	s_nop 1
	v_permlane32_swap_b32_e32 v0, v2
	v_max3_f32 v2, v240, v0, v2
	v_sub_f32_e32 v0, v240, v2
	v_exp_f32_e32 v0, v0
	v_cmp_neq_f32_e32 vcc, v2, v240
	s_cbranch_vccz .LBB0_1976
	v_pk_mul_f32 v[78:79], v[78:79], v[0:1] op_sel_hi:[1,0]
	v_pk_mul_f32 v[76:77], v[76:77], v[0:1] op_sel_hi:[1,0]
	v_pk_mul_f32 v[74:75], v[74:75], v[0:1] op_sel_hi:[1,0]
	v_pk_mul_f32 v[72:73], v[72:73], v[0:1] op_sel_hi:[1,0]
	v_pk_mul_f32 v[70:71], v[70:71], v[0:1] op_sel_hi:[1,0]
	v_pk_mul_f32 v[68:69], v[68:69], v[0:1] op_sel_hi:[1,0]
	v_pk_mul_f32 v[66:67], v[66:67], v[0:1] op_sel_hi:[1,0]
	v_pk_mul_f32 v[64:65], v[64:65], v[0:1] op_sel_hi:[1,0]
	v_pk_mul_f32 v[62:63], v[62:63], v[0:1] op_sel_hi:[1,0]
	v_pk_mul_f32 v[60:61], v[60:61], v[0:1] op_sel_hi:[1,0]
	v_pk_mul_f32 v[58:59], v[58:59], v[0:1] op_sel_hi:[1,0]
	v_pk_mul_f32 v[56:57], v[56:57], v[0:1] op_sel_hi:[1,0]
	v_pk_mul_f32 v[54:55], v[54:55], v[0:1] op_sel_hi:[1,0]
	v_pk_mul_f32 v[52:53], v[52:53], v[0:1] op_sel_hi:[1,0]
	v_pk_mul_f32 v[50:51], v[50:51], v[0:1] op_sel_hi:[1,0]
	v_pk_mul_f32 v[48:49], v[48:49], v[0:1] op_sel_hi:[1,0]
	v_pk_mul_f32 v[46:47], v[46:47], v[0:1] op_sel_hi:[1,0]
	v_pk_mul_f32 v[44:45], v[44:45], v[0:1] op_sel_hi:[1,0]
	v_pk_mul_f32 v[42:43], v[42:43], v[0:1] op_sel_hi:[1,0]
	v_pk_mul_f32 v[40:41], v[40:41], v[0:1] op_sel_hi:[1,0]
	v_pk_mul_f32 v[38:39], v[38:39], v[0:1] op_sel_hi:[1,0]
	v_pk_mul_f32 v[36:37], v[36:37], v[0:1] op_sel_hi:[1,0]
	v_pk_mul_f32 v[34:35], v[34:35], v[0:1] op_sel_hi:[1,0]
	v_pk_mul_f32 v[32:33], v[32:33], v[0:1] op_sel_hi:[1,0]
	v_pk_mul_f32 v[30:31], v[30:31], v[0:1] op_sel_hi:[1,0]
	v_pk_mul_f32 v[28:29], v[28:29], v[0:1] op_sel_hi:[1,0]
	v_pk_mul_f32 v[26:27], v[26:27], v[0:1] op_sel_hi:[1,0]
	v_pk_mul_f32 v[24:25], v[24:25], v[0:1] op_sel_hi:[1,0]
	v_pk_mul_f32 v[22:23], v[22:23], v[0:1] op_sel_hi:[1,0]
	v_pk_mul_f32 v[20:21], v[20:21], v[0:1] op_sel_hi:[1,0]
	v_pk_mul_f32 v[18:19], v[18:19], v[0:1] op_sel_hi:[1,0]
	v_pk_mul_f32 v[16:17], v[16:17], v[0:1] op_sel_hi:[1,0]

; DI unsigned pk2(float lo, float hi) { f32x2 v = {lo, hi}; bf16x2_t b = __builtin_convertvector(v, bf16x2_t); return __builtin_bit_cast(unsigned, b); }
; DI float siluf(float x) { return x * __builtin_amdgcn_rcpf(1.f + __expf(-x)); }
;     DI void operator()(const f32x4 (&acc)[2][2][4][2], const pg8::Unit& u, int wr, int wc, int fr, int fq) const {
; #pragma unroll
;         for (int ai = 0; ai < 2; ++ai)
; #pragma unroll
;             for (int m = 0; m < 4; ++m) { const int r = u.pm * 256 + ai * 128 + wr * 64 + m * 16 + fr; bf16_t* rowp = H + (size_t)r * DFF + u.pn * 128 + wc * 32 + 8 * fq; float v[8]; const float sr = rss ? rsqrtf(rss[r] * (1.f / D) + 1e-6f) : 1.f;
; #pragma unroll
;                 for (int n = 0; n < 2; ++n)
; #pragma unroll
;                     for (int e = 0; e < 4; ++e) v[4 * n + e] = siluf(acc[ai][0][m][n][e] * sr) * (acc[ai][1][m][n][e] * sr);
;                 u32x4 w; w.x = pk2(v[0], v[1]); w.y = pk2(v[2], v[3]); w.z = pk2(v[4], v[5]); w.w = pk2(v[6], v[7]); *(u32x4*)rowp = w; }
;     }
.LBB0_2280:
	s_lshl_b32 s0, s0, 8
	v_add_u32_e32 v198, s0, v154
	v_ashrrev_i32_e32 v199, 31, v198
	v_lshl_add_u64 v[196:197], v[198:199], 2, s[8:9]
	v_add_u32_e32 v194, s0, v153
	v_ashrrev_i32_e32 v195, 31, v194
	v_lshl_add_u64 v[192:193], v[194:195], 2, s[8:9]
	v_add_u32_e32 v190, s0, v152
	v_ashrrev_i32_e32 v191, 31, v190
	v_lshl_add_u64 v[188:189], v[190:191], 2, s[8:9]
	v_add_u32_e32 v186, s0, v150
	v_add_u32_e32 v216, 0xb0, v186
	v_ashrrev_i32_e32 v217, 31, v216
	v_lshl_add_u64 v[214:215], v[216:217], 2, s[8:9]
	v_add_u32_e32 v210, 0xa0, v186
	v_ashrrev_i32_e32 v211, 31, v210
	v_lshl_add_u64 v[208:209], v[210:211], 2, s[8:9]
	v_add_u32_e32 v206, 0x90, v186
	v_ashrrev_i32_e32 v207, 31, v206
	v_lshl_add_u64 v[204:205], v[206:207], 2, s[8:9]
	v_add_u32_e32 v202, 0x80, v186
	v_ashrrev_i32_e32 v203, 31, v202
	v_lshl_add_u64 v[200:201], v[202:203], 2, s[8:9]
	v_ashrrev_i32_e32 v187, 31, v186
	v_lshl_add_u64 v[184:185], v[186:187], 2, s[8:9]
	global_load_dword v176, v[184:185], off
	global_load_dword v177, v[188:189], off
	global_load_dword v178, v[192:193], off
	global_load_dword v179, v[196:197], off
	global_load_dword v180, v[200:201], off
	global_load_dword v181, v[204:205], off
	global_load_dword v182, v[208:209], off
	global_load_dword v183, v[214:215], off
	s_nop 0
	s_nop 0
	s_nop 0
	v_readlane_b32 s18, v247, 62
	v_readlane_b32 s19, v247, 63
	s_waitcnt vmcnt(7)
	v_fmamk_f32 v149, v176, 0x3a800000, v158
	v_mul_f32_e32 v159, 0x4b800000, v149
	v_cmp_gt_f32_e32 vcc, s50, v149
	v_mov_b64_e32 v[146:147], s[18:19]
	s_lshl_b32 s18, s1, 7
	v_cndmask_b32_e32 v149, v149, v159, vcc
	v_rsq_f32_e32 v149, v149
	s_ashr_i32 s19, s18, 31
	v_mad_i64_i32 v[162:163], s[26:27], v186, s49, v[146:147]
	v_mul_f32_e32 v159, 0x45800000, v149
	v_cndmask_b32_e32 v166, v149, v159, vcc
	v_pk_mul_f32 v[124:125], v[124:125], v[166:167] op_sel_hi:[1,0]
	v_pk_mul_f32 v[126:127], v[126:127], v[166:167] op_sel_hi:[1,0]
	v_pk_mul_f32 v[120:121], v[120:121], v[166:167] op_sel_hi:[1,0]
	v_pk_mul_f32 v[122:123], v[122:123], v[166:167] op_sel_hi:[1,0]
	v_pk_mul_f32 v[116:117], v[116:117], v[166:167] op_sel_hi:[1,0]
	v_pk_mul_f32 v[118:119], v[118:119], v[166:167] op_sel_hi:[1,0]
	v_pk_mul_f32 v[112:113], v[112:113], v[166:167] op_sel_hi:[1,0]
	v_pk_mul_f32 v[114:115], v[114:115], v[166:167] op_sel_hi:[1,0]
	v_mul_f32_e32 v149, 0xbfb8aa3b, v124
	v_mul_f32_e32 v159, 0xbfb8aa3b, v125
	v_mul_f32_e32 v161, 0xbfb8aa3b, v126
	v_mul_f32_e32 v166, 0xbfb8aa3b, v127
	v_mul_f32_e32 v167, 0xbfb8aa3b, v120
	v_mul_f32_e32 v168, 0xbfb8aa3b, v121
	v_mul_f32_e32 v169, 0xbfb8aa3b, v122
	v_mul_f32_e32 v170, 0xbfb8aa3b, v123
	v_exp_f32_e32 v149, v149
	v_exp_f32_e32 v159, v159
	v_exp_f32_e32 v161, v161
	v_exp_f32_e32 v166, v166
	v_exp_f32_e32 v167, v167
	v_exp_f32_e32 v168, v168
	v_exp_f32_e32 v169, v169
	v_exp_f32_e32 v170, v170
	v_add_f32_e32 v149, 1.0, v149
	v_add_f32_e32 v159, 1.0, v159
	v_add_f32_e32 v161, 1.0, v161
	v_add_f32_e32 v171, 1.0, v166
	v_add_f32_e32 v172, 1.0, v167
	v_add_f32_e32 v173, 1.0, v168
	v_add_f32_e32 v174, 1.0, v169
	v_add_f32_e32 v175, 1.0, v170
	v_rcp_f32_e32 v166, v149
	v_rcp_f32_e32 v167, v159
	v_rcp_f32_e32 v168, v161
	v_rcp_f32_e32 v169, v171
	v_rcp_f32_e32 v170, v172
	v_rcp_f32_e32 v171, v173
	v_rcp_f32_e32 v172, v174
	v_rcp_f32_e32 v173, v175
	s_lshl_b64 s[18:19], s[18:19], 1
	v_lshl_add_u64 v[162:163], v[162:163], 0, s[18:19]
	v_pk_mul_f32 v[124:125], v[124:125], v[166:167]
	v_pk_mul_f32 v[126:127], v[126:127], v[168:169]
	v_pk_mul_f32 v[120:121], v[120:121], v[170:171]
	v_pk_mul_f32 v[122:123], v[122:123], v[172:173]
	v_lshl_add_u64 v[162:163], v[162:163], 0, s[6:7]
	v_pk_mul_f32 v[116:117], v[116:117], v[124:125]
	v_pk_mul_f32 v[118:119], v[118:119], v[126:127]
	v_pk_mul_f32 v[120:121], v[112:113], v[120:121]
	v_pk_mul_f32 v[122:123], v[114:115], v[122:123]
	v_lshl_add_u64 v[162:163], v[162:163], 0, v[136:137]
	v_cvt_pk_bf16_f32 v112, v116, v117
	v_cvt_pk_bf16_f32 v113, v118, v119
	v_cvt_pk_bf16_f32 v114, v120, v121
	v_cvt_pk_bf16_f32 v115, v122, v123
	global_store_dwordx4 v[162:163], v[112:115], off
	s_nop 0
	s_waitcnt vmcnt(7)
	v_fmamk_f32 v116, v177, 0x3a800000, v158
	v_mul_f32_e32 v117, 0x4b800000, v116
	v_cmp_gt_f32_e32 vcc, s50, v116
	s_nop 0
	s_nop 0
	v_cndmask_b32_e32 v116, v116, v117, vcc
	v_rsq_f32_e32 v118, v116
	s_nop 0
	v_mad_i64_i32 v[114:115], s[26:27], v190, s49, v[146:147]
	v_mul_f32_e32 v113, 0x45800000, v118
	v_cndmask_b32_e32 v118, v118, v113, vcc
	v_pk_mul_f32 v[108:109], v[108:109], v[118:119] op_sel_hi:[1,0]
	v_pk_mul_f32 v[110:111], v[110:111], v[118:119] op_sel_hi:[1,0]
	v_pk_mul_f32 v[104:105], v[104:105], v[118:119] op_sel_hi:[1,0]
	v_pk_mul_f32 v[106:107], v[106:107], v[118:119] op_sel_hi:[1,0]
	v_pk_mul_f32 v[100:101], v[100:101], v[118:119] op_sel_hi:[1,0]
	v_pk_mul_f32 v[102:103], v[102:103], v[118:119] op_sel_hi:[1,0]
	v_pk_mul_f32 v[96:97], v[96:97], v[118:119] op_sel_hi:[1,0]
	v_pk_mul_f32 v[98:99], v[98:99], v[118:119] op_sel_hi:[1,0]
	v_mul_f32_e32 v113, 0xbfb8aa3b, v108
	v_mul_f32_e32 v118, 0xbfb8aa3b, v109
	v_mul_f32_e32 v119, 0xbfb8aa3b, v110
	v_mul_f32_e32 v120, 0xbfb8aa3b, v111
	v_mul_f32_e32 v121, 0xbfb8aa3b, v104
	v_mul_f32_e32 v122, 0xbfb8aa3b, v105
	v_mul_f32_e32 v123, 0xbfb8aa3b, v106
	v_mul_f32_e32 v124, 0xbfb8aa3b, v107
	v_exp_f32_e32 v113, v113
	v_exp_f32_e32 v118, v118
	v_exp_f32_e32 v119, v119
	v_exp_f32_e32 v120, v120
	v_exp_f32_e32 v121, v121
	v_exp_f32_e32 v122, v122
	v_exp_f32_e32 v123, v123
	v_exp_f32_e32 v124, v124
	v_add_f32_e32 v113, 1.0, v113
	v_add_f32_e32 v125, 1.0, v118
	v_add_f32_e32 v126, 1.0, v119
	v_add_f32_e32 v127, 1.0, v120
	v_add_f32_e32 v149, 1.0, v121
	v_add_f32_e32 v159, 1.0, v122
	v_add_f32_e32 v160, 1.0, v123
	v_add_f32_e32 v161, 1.0, v124
	v_rcp_f32_e32 v118, v113
	v_rcp_f32_e32 v119, v125
	v_rcp_f32_e32 v120, v126
	v_rcp_f32_e32 v121, v127
	v_rcp_f32_e32 v122, v149
	v_rcp_f32_e32 v123, v159
	v_rcp_f32_e32 v124, v160
	v_rcp_f32_e32 v125, v161
	v_lshl_add_u64 v[114:115], v[114:115], 0, s[18:19]
	v_pk_mul_f32 v[108:109], v[108:109], v[118:119]
	v_pk_mul_f32 v[110:111], v[110:111], v[120:121]
	v_pk_mul_f32 v[104:105], v[104:105], v[122:123]
	v_pk_mul_f32 v[106:107], v[106:107], v[124:125]
	v_lshl_add_u64 v[114:115], v[114:115], 0, s[6:7]
	v_pk_mul_f32 v[100:101], v[100:101], v[108:109]
	v_pk_mul_f32 v[102:103], v[102:103], v[110:111]
	v_pk_mul_f32 v[104:105], v[96:97], v[104:105]
	v_pk_mul_f32 v[106:107], v[98:99], v[106:107]
	v_lshl_add_u64 v[114:115], v[114:115], 0, v[136:137]
	v_cvt_pk_bf16_f32 v96, v100, v101
	v_cvt_pk_bf16_f32 v97, v102, v103
	v_cvt_pk_bf16_f32 v98, v104, v105
	v_cvt_pk_bf16_f32 v99, v106, v107
	global_store_dwordx4 v[114:115], v[96:99], off
	s_nop 0
	s_waitcnt vmcnt(7)
; DI unsigned pk2(float lo, float hi) { f32x2 v = {lo, hi}; bf16x2_t b = __builtin_convertvector(v, bf16x2_t); return __builtin_bit_cast(unsigned, b); }
; DI float siluf(float x) { return x * __builtin_amdgcn_rcpf(1.f + __expf(-x)); }
;     DI void operator()(const f32x4 (&acc)[2][2][4][2], const pg8::Unit& u, int wr, int wc, int fr, int fq) const {
; #pragma unroll
;         for (int ai = 0; ai < 2; ++ai)
; #pragma unroll
;             for (int m = 0; m < 4; ++m) { const int r = u.pm * 256 + ai * 128 + wr * 64 + m * 16 + fr; bf16_t* rowp = H + (size_t)r * DFF + u.pn * 128 + wc * 32 + 8 * fq; float v[8]; const float sr = rss ? rsqrtf(rss[r] * (1.f / D) + 1e-6f) : 1.f;
; #pragma unroll
;                 for (int n = 0; n < 2; ++n)
; #pragma unroll
;                     for (int e = 0; e < 4; ++e) v[4 * n + e] = siluf(acc[ai][0][m][n][e] * sr) * (acc[ai][1][m][n][e] * sr);
;                 u32x4 w; w.x = pk2(v[0], v[1]); w.y = pk2(v[2], v[3]); w.z = pk2(v[4], v[5]); w.w = pk2(v[6], v[7]); *(u32x4*)rowp = w; }
;     }
	v_fmamk_f32 v100, v178, 0x3a800000, v158
	v_mul_f32_e32 v101, 0x4b800000, v100
	v_cmp_gt_f32_e32 vcc, s50, v100
	s_nop 0
	s_nop 0
	v_cndmask_b32_e32 v100, v100, v101, vcc
	v_rsq_f32_e32 v102, v100
	s_nop 0
	v_mad_i64_i32 v[98:99], s[0:1], v194, s49, v[146:147]
	v_mul_f32_e32 v97, 0x45800000, v102
	v_cndmask_b32_e32 v102, v102, v97, vcc
	v_pk_mul_f32 v[92:93], v[92:93], v[102:103] op_sel_hi:[1,0]
	v_pk_mul_f32 v[94:95], v[94:95], v[102:103] op_sel_hi:[1,0]
	v_pk_mul_f32 v[88:89], v[88:89], v[102:103] op_sel_hi:[1,0]
	v_pk_mul_f32 v[90:91], v[90:91], v[102:103] op_sel_hi:[1,0]
	v_pk_mul_f32 v[84:85], v[84:85], v[102:103] op_sel_hi:[1,0]
	v_pk_mul_f32 v[86:87], v[86:87], v[102:103] op_sel_hi:[1,0]
	v_pk_mul_f32 v[80:81], v[80:81], v[102:103] op_sel_hi:[1,0]
	v_pk_mul_f32 v[82:83], v[82:83], v[102:103] op_sel_hi:[1,0]
	v_mul_f32_e32 v97, 0xbfb8aa3b, v92
	v_mul_f32_e32 v102, 0xbfb8aa3b, v93
	v_mul_f32_e32 v103, 0xbfb8aa3b, v94
	v_mul_f32_e32 v104, 0xbfb8aa3b, v95
	v_mul_f32_e32 v105, 0xbfb8aa3b, v88
	v_mul_f32_e32 v106, 0xbfb8aa3b, v89
	v_mul_f32_e32 v107, 0xbfb8aa3b, v90
	v_mul_f32_e32 v108, 0xbfb8aa3b, v91
	v_exp_f32_e32 v97, v97
	v_exp_f32_e32 v102, v102
	v_exp_f32_e32 v103, v103
	v_exp_f32_e32 v104, v104
	v_exp_f32_e32 v105, v105
	v_exp_f32_e32 v106, v106
	v_exp_f32_e32 v107, v107
	v_exp_f32_e32 v108, v108
	v_add_f32_e32 v97, 1.0, v97
	v_add_f32_e32 v109, 1.0, v102
	v_add_f32_e32 v110, 1.0, v103
	v_add_f32_e32 v111, 1.0, v104
	v_add_f32_e32 v112, 1.0, v105
	v_add_f32_e32 v113, 1.0, v106
	v_add_f32_e32 v114, 1.0, v107
	v_add_f32_e32 v115, 1.0, v108
	v_rcp_f32_e32 v102, v97
	v_rcp_f32_e32 v103, v109
	v_rcp_f32_e32 v104, v110
	v_rcp_f32_e32 v105, v111
	v_rcp_f32_e32 v106, v112
	v_rcp_f32_e32 v107, v113
	v_rcp_f32_e32 v108, v114
	v_rcp_f32_e32 v109, v115
	v_lshl_add_u64 v[98:99], v[98:99], 0, s[18:19]
	v_pk_mul_f32 v[92:93], v[92:93], v[102:103]
	v_pk_mul_f32 v[94:95], v[94:95], v[104:105]
	v_pk_mul_f32 v[88:89], v[88:89], v[106:107]
	v_pk_mul_f32 v[90:91], v[90:91], v[108:109]
	v_lshl_add_u64 v[98:99], v[98:99], 0, s[6:7]
	v_pk_mul_f32 v[84:85], v[84:85], v[92:93]
	v_pk_mul_f32 v[86:87], v[86:87], v[94:95]
	v_pk_mul_f32 v[88:89], v[80:81], v[88:89]
	v_pk_mul_f32 v[90:91], v[82:83], v[90:91]
	v_lshl_add_u64 v[98:99], v[98:99], 0, v[136:137]
	v_cvt_pk_bf16_f32 v80, v84, v85
	v_cvt_pk_bf16_f32 v81, v86, v87
	v_cvt_pk_bf16_f32 v82, v88, v89
	v_cvt_pk_bf16_f32 v83, v90, v91
	global_store_dwordx4 v[98:99], v[80:83], off
	s_nop 0
	s_waitcnt vmcnt(7)
	v_fmamk_f32 v84, v179, 0x3a800000, v158
	v_mul_f32_e32 v85, 0x4b800000, v84
	v_cmp_gt_f32_e32 vcc, s50, v84
	s_nop 0
	s_nop 0
	v_cndmask_b32_e32 v84, v84, v85, vcc
	v_rsq_f32_e32 v86, v84
	s_nop 0
	v_mad_i64_i32 v[80:81], s[0:1], v198, s49, v[146:147]
	v_mul_f32_e32 v83, 0x45800000, v86
	v_cndmask_b32_e32 v86, v86, v83, vcc
	v_pk_mul_f32 v[76:77], v[76:77], v[86:87] op_sel_hi:[1,0]
	v_pk_mul_f32 v[78:79], v[78:79], v[86:87] op_sel_hi:[1,0]
	v_pk_mul_f32 v[72:73], v[72:73], v[86:87] op_sel_hi:[1,0]
	v_pk_mul_f32 v[74:75], v[74:75], v[86:87] op_sel_hi:[1,0]
	v_pk_mul_f32 v[68:69], v[68:69], v[86:87] op_sel_hi:[1,0]
	v_pk_mul_f32 v[70:71], v[70:71], v[86:87] op_sel_hi:[1,0]
	v_pk_mul_f32 v[64:65], v[64:65], v[86:87] op_sel_hi:[1,0]
	v_pk_mul_f32 v[66:67], v[66:67], v[86:87] op_sel_hi:[1,0]
	v_mul_f32_e32 v83, 0xbfb8aa3b, v76
	v_mul_f32_e32 v86, 0xbfb8aa3b, v77
	v_mul_f32_e32 v87, 0xbfb8aa3b, v78
	v_mul_f32_e32 v88, 0xbfb8aa3b, v79
	v_mul_f32_e32 v89, 0xbfb8aa3b, v72
	v_mul_f32_e32 v90, 0xbfb8aa3b, v73
	v_mul_f32_e32 v91, 0xbfb8aa3b, v74
	v_mul_f32_e32 v92, 0xbfb8aa3b, v75
	v_exp_f32_e32 v83, v83
	v_exp_f32_e32 v86, v86
	v_exp_f32_e32 v87, v87
	v_exp_f32_e32 v88, v88
	v_exp_f32_e32 v89, v89
	v_exp_f32_e32 v90, v90
	v_exp_f32_e32 v91, v91
	v_exp_f32_e32 v92, v92
	v_add_f32_e32 v83, 1.0, v83
	v_add_f32_e32 v93, 1.0, v86
	v_add_f32_e32 v94, 1.0, v87
	v_add_f32_e32 v95, 1.0, v88
	v_add_f32_e32 v96, 1.0, v89
	v_add_f32_e32 v97, 1.0, v90
	v_add_f32_e32 v98, 1.0, v91
	v_add_f32_e32 v99, 1.0, v92
	v_rcp_f32_e32 v86, v83
	v_rcp_f32_e32 v87, v93
	v_rcp_f32_e32 v88, v94
	v_rcp_f32_e32 v89, v95
	v_rcp_f32_e32 v90, v96
	v_rcp_f32_e32 v91, v97
	v_rcp_f32_e32 v92, v98
	v_rcp_f32_e32 v93, v99
	v_lshl_add_u64 v[80:81], v[80:81], 0, s[18:19]
	v_pk_mul_f32 v[76:77], v[76:77], v[86:87]
	v_pk_mul_f32 v[78:79], v[78:79], v[88:89]
	v_pk_mul_f32 v[72:73], v[72:73], v[90:91]
	v_pk_mul_f32 v[74:75], v[74:75], v[92:93]
	v_lshl_add_u64 v[80:81], v[80:81], 0, s[6:7]
	v_pk_mul_f32 v[68:69], v[68:69], v[76:77]
	v_pk_mul_f32 v[70:71], v[70:71], v[78:79]
	v_pk_mul_f32 v[72:73], v[64:65], v[72:73]
	v_pk_mul_f32 v[74:75], v[66:67], v[74:75]
	v_lshl_add_u64 v[80:81], v[80:81], 0, v[136:137]
	v_cvt_pk_bf16_f32 v64, v68, v69
	v_cvt_pk_bf16_f32 v65, v70, v71
	v_cvt_pk_bf16_f32 v66, v72, v73
	v_cvt_pk_bf16_f32 v67, v74, v75
	global_store_dwordx4 v[80:81], v[64:67], off
	s_nop 0
	s_waitcnt vmcnt(7)
; DI unsigned pk2(float lo, float hi) { f32x2 v = {lo, hi}; bf16x2_t b = __builtin_convertvector(v, bf16x2_t); return __builtin_bit_cast(unsigned, b); }
; DI float siluf(float x) { return x * __builtin_amdgcn_rcpf(1.f + __expf(-x)); }
;     DI void operator()(const f32x4 (&acc)[2][2][4][2], const pg8::Unit& u, int wr, int wc, int fr, int fq) const {
; #pragma unroll
;         for (int ai = 0; ai < 2; ++ai)
; #pragma unroll
;             for (int m = 0; m < 4; ++m) { const int r = u.pm * 256 + ai * 128 + wr * 64 + m * 16 + fr; bf16_t* rowp = H + (size_t)r * DFF + u.pn * 128 + wc * 32 + 8 * fq; float v[8]; const float sr = rss ? rsqrtf(rss[r] * (1.f / D) + 1e-6f) : 1.f;
; #pragma unroll
;                 for (int n = 0; n < 2; ++n)
; #pragma unroll
;                     for (int e = 0; e < 4; ++e) v[4 * n + e] = siluf(acc[ai][0][m][n][e] * sr) * (acc[ai][1][m][n][e] * sr);
;                 u32x4 w; w.x = pk2(v[0], v[1]); w.y = pk2(v[2], v[3]); w.z = pk2(v[4], v[5]); w.w = pk2(v[6], v[7]); *(u32x4*)rowp = w; }
;     }
	v_fmamk_f32 v68, v180, 0x3a800000, v158
	v_mul_f32_e32 v69, 0x4b800000, v68
	v_cmp_gt_f32_e32 vcc, s50, v68
	s_nop 0
	s_nop 0
	v_cndmask_b32_e32 v68, v68, v69, vcc
	v_rsq_f32_e32 v70, v68
	s_nop 0
	v_mad_i64_i32 v[66:67], s[0:1], v202, s49, v[146:147]
	v_mul_f32_e32 v65, 0x45800000, v70
	v_cndmask_b32_e32 v70, v70, v65, vcc
	v_pk_mul_f32 v[60:61], v[60:61], v[70:71] op_sel_hi:[1,0]
	v_pk_mul_f32 v[62:63], v[62:63], v[70:71] op_sel_hi:[1,0]
	v_pk_mul_f32 v[56:57], v[56:57], v[70:71] op_sel_hi:[1,0]
	v_pk_mul_f32 v[58:59], v[58:59], v[70:71] op_sel_hi:[1,0]
	v_pk_mul_f32 v[52:53], v[52:53], v[70:71] op_sel_hi:[1,0]
	v_pk_mul_f32 v[54:55], v[54:55], v[70:71] op_sel_hi:[1,0]
	v_pk_mul_f32 v[48:49], v[48:49], v[70:71] op_sel_hi:[1,0]
	v_pk_mul_f32 v[50:51], v[50:51], v[70:71] op_sel_hi:[1,0]
	v_mul_f32_e32 v65, 0xbfb8aa3b, v60
	v_mul_f32_e32 v70, 0xbfb8aa3b, v61
	v_mul_f32_e32 v71, 0xbfb8aa3b, v62
	v_mul_f32_e32 v72, 0xbfb8aa3b, v63
	v_mul_f32_e32 v73, 0xbfb8aa3b, v56
	v_mul_f32_e32 v74, 0xbfb8aa3b, v57
	v_mul_f32_e32 v75, 0xbfb8aa3b, v58
	v_mul_f32_e32 v76, 0xbfb8aa3b, v59
	v_exp_f32_e32 v65, v65
	v_exp_f32_e32 v70, v70
	v_exp_f32_e32 v71, v71
	v_exp_f32_e32 v72, v72
	v_exp_f32_e32 v73, v73
	v_exp_f32_e32 v74, v74
	v_exp_f32_e32 v75, v75
	v_exp_f32_e32 v76, v76
	v_add_f32_e32 v65, 1.0, v65
	v_add_f32_e32 v77, 1.0, v70
	v_add_f32_e32 v78, 1.0, v71
	v_add_f32_e32 v79, 1.0, v72
	v_add_f32_e32 v80, 1.0, v73
	v_add_f32_e32 v81, 1.0, v74
	v_add_f32_e32 v82, 1.0, v75
	v_add_f32_e32 v83, 1.0, v76
	v_rcp_f32_e32 v70, v65
	v_rcp_f32_e32 v71, v77
	v_rcp_f32_e32 v72, v78
	v_rcp_f32_e32 v73, v79
	v_rcp_f32_e32 v74, v80
	v_rcp_f32_e32 v75, v81
	v_rcp_f32_e32 v76, v82
	v_rcp_f32_e32 v77, v83
	v_lshl_add_u64 v[66:67], v[66:67], 0, s[18:19]
	v_pk_mul_f32 v[60:61], v[60:61], v[70:71]
	v_pk_mul_f32 v[62:63], v[62:63], v[72:73]
	v_pk_mul_f32 v[56:57], v[56:57], v[74:75]
	v_pk_mul_f32 v[58:59], v[58:59], v[76:77]
	v_lshl_add_u64 v[66:67], v[66:67], 0, s[6:7]
	v_pk_mul_f32 v[52:53], v[52:53], v[60:61]
	v_pk_mul_f32 v[54:55], v[54:55], v[62:63]
	v_pk_mul_f32 v[56:57], v[48:49], v[56:57]
	v_pk_mul_f32 v[58:59], v[50:51], v[58:59]
	v_lshl_add_u64 v[66:67], v[66:67], 0, v[136:137]
	v_cvt_pk_bf16_f32 v48, v52, v53
	v_cvt_pk_bf16_f32 v49, v54, v55
	v_cvt_pk_bf16_f32 v50, v56, v57
	v_cvt_pk_bf16_f32 v51, v58, v59
	global_store_dwordx4 v[66:67], v[48:51], off
	s_nop 0
	s_waitcnt vmcnt(7)
	v_fmamk_f32 v52, v181, 0x3a800000, v158
	v_mul_f32_e32 v53, 0x4b800000, v52
	v_cmp_gt_f32_e32 vcc, s50, v52
	s_nop 0
	s_nop 0
	v_cndmask_b32_e32 v52, v52, v53, vcc
	v_rsq_f32_e32 v54, v52
	s_nop 0
	v_mad_i64_i32 v[50:51], s[0:1], v206, s49, v[146:147]
	v_mul_f32_e32 v49, 0x45800000, v54
	v_cndmask_b32_e32 v54, v54, v49, vcc
	v_pk_mul_f32 v[44:45], v[44:45], v[54:55] op_sel_hi:[1,0]
	v_pk_mul_f32 v[46:47], v[46:47], v[54:55] op_sel_hi:[1,0]
	v_pk_mul_f32 v[40:41], v[40:41], v[54:55] op_sel_hi:[1,0]
	v_pk_mul_f32 v[42:43], v[42:43], v[54:55] op_sel_hi:[1,0]
	v_pk_mul_f32 v[36:37], v[36:37], v[54:55] op_sel_hi:[1,0]
	v_pk_mul_f32 v[38:39], v[38:39], v[54:55] op_sel_hi:[1,0]
	v_pk_mul_f32 v[32:33], v[32:33], v[54:55] op_sel_hi:[1,0]
	v_pk_mul_f32 v[34:35], v[34:35], v[54:55] op_sel_hi:[1,0]
	v_mul_f32_e32 v49, 0xbfb8aa3b, v44
	v_mul_f32_e32 v54, 0xbfb8aa3b, v45
	v_mul_f32_e32 v55, 0xbfb8aa3b, v46
	v_mul_f32_e32 v56, 0xbfb8aa3b, v47
	v_mul_f32_e32 v57, 0xbfb8aa3b, v40
	v_mul_f32_e32 v58, 0xbfb8aa3b, v41
	v_mul_f32_e32 v59, 0xbfb8aa3b, v42
	v_mul_f32_e32 v60, 0xbfb8aa3b, v43
	v_exp_f32_e32 v49, v49
	v_exp_f32_e32 v54, v54
	v_exp_f32_e32 v55, v55
	v_exp_f32_e32 v56, v56
	v_exp_f32_e32 v57, v57
	v_exp_f32_e32 v58, v58
	v_exp_f32_e32 v59, v59
	v_exp_f32_e32 v60, v60
	v_add_f32_e32 v49, 1.0, v49
	v_add_f32_e32 v61, 1.0, v54
	v_add_f32_e32 v62, 1.0, v55
	v_add_f32_e32 v63, 1.0, v56
	v_add_f32_e32 v64, 1.0, v57
	v_add_f32_e32 v65, 1.0, v58
	v_add_f32_e32 v66, 1.0, v59
	v_add_f32_e32 v67, 1.0, v60
	v_rcp_f32_e32 v54, v49
	v_rcp_f32_e32 v55, v61
	v_rcp_f32_e32 v56, v62
	v_rcp_f32_e32 v57, v63
	v_rcp_f32_e32 v58, v64
	v_rcp_f32_e32 v59, v65
	v_rcp_f32_e32 v60, v66
	v_rcp_f32_e32 v61, v67
	v_lshl_add_u64 v[50:51], v[50:51], 0, s[18:19]
	v_pk_mul_f32 v[44:45], v[44:45], v[54:55]
	v_pk_mul_f32 v[46:47], v[46:47], v[56:57]
	v_pk_mul_f32 v[40:41], v[40:41], v[58:59]
	v_pk_mul_f32 v[42:43], v[42:43], v[60:61]
	v_lshl_add_u64 v[50:51], v[50:51], 0, s[6:7]
	v_pk_mul_f32 v[36:37], v[36:37], v[44:45]
	v_pk_mul_f32 v[38:39], v[38:39], v[46:47]
	v_pk_mul_f32 v[40:41], v[32:33], v[40:41]
	v_pk_mul_f32 v[42:43], v[34:35], v[42:43]
	v_lshl_add_u64 v[50:51], v[50:51], 0, v[136:137]
	v_cvt_pk_bf16_f32 v32, v36, v37
	v_cvt_pk_bf16_f32 v33, v38, v39
	v_cvt_pk_bf16_f32 v34, v40, v41
	v_cvt_pk_bf16_f32 v35, v42, v43
	global_store_dwordx4 v[50:51], v[32:35], off
	s_nop 0
	s_waitcnt vmcnt(7)
; DI unsigned pk2(float lo, float hi) { f32x2 v = {lo, hi}; bf16x2_t b = __builtin_convertvector(v, bf16x2_t); return __builtin_bit_cast(unsigned, b); }
; DI float siluf(float x) { return x * __builtin_amdgcn_rcpf(1.f + __expf(-x)); }
;     DI void operator()(const f32x4 (&acc)[2][2][4][2], const pg8::Unit& u, int wr, int wc, int fr, int fq) const {
; #pragma unroll
;         for (int ai = 0; ai < 2; ++ai)
; #pragma unroll
;             for (int m = 0; m < 4; ++m) { const int r = u.pm * 256 + ai * 128 + wr * 64 + m * 16 + fr; bf16_t* rowp = H + (size_t)r * DFF + u.pn * 128 + wc * 32 + 8 * fq; float v[8]; const float sr = rss ? rsqrtf(rss[r] * (1.f / D) + 1e-6f) : 1.f;
; #pragma unroll
;                 for (int n = 0; n < 2; ++n)
; #pragma unroll
;                     for (int e = 0; e < 4; ++e) v[4 * n + e] = siluf(acc[ai][0][m][n][e] * sr) * (acc[ai][1][m][n][e] * sr);
;                 u32x4 w; w.x = pk2(v[0], v[1]); w.y = pk2(v[2], v[3]); w.z = pk2(v[4], v[5]); w.w = pk2(v[6], v[7]); *(u32x4*)rowp = w; }
;     }
	v_fmamk_f32 v36, v182, 0x3a800000, v158
	v_mul_f32_e32 v37, 0x4b800000, v36
	v_cmp_gt_f32_e32 vcc, s50, v36
	s_nop 0
	s_nop 0
	v_cndmask_b32_e32 v36, v36, v37, vcc
	v_rsq_f32_e32 v38, v36
	s_nop 0
	v_mad_i64_i32 v[34:35], s[0:1], v210, s49, v[146:147]
	v_mul_f32_e32 v33, 0x45800000, v38
	v_cndmask_b32_e32 v38, v38, v33, vcc
	v_pk_mul_f32 v[28:29], v[28:29], v[38:39] op_sel_hi:[1,0]
	v_pk_mul_f32 v[30:31], v[30:31], v[38:39] op_sel_hi:[1,0]
	v_pk_mul_f32 v[24:25], v[24:25], v[38:39] op_sel_hi:[1,0]
	v_pk_mul_f32 v[26:27], v[26:27], v[38:39] op_sel_hi:[1,0]
	v_pk_mul_f32 v[20:21], v[20:21], v[38:39] op_sel_hi:[1,0]
	v_pk_mul_f32 v[22:23], v[22:23], v[38:39] op_sel_hi:[1,0]
	v_pk_mul_f32 v[16:17], v[16:17], v[38:39] op_sel_hi:[1,0]
	v_pk_mul_f32 v[18:19], v[18:19], v[38:39] op_sel_hi:[1,0]
	v_mul_f32_e32 v33, 0xbfb8aa3b, v28
	v_mul_f32_e32 v38, 0xbfb8aa3b, v29
	v_mul_f32_e32 v39, 0xbfb8aa3b, v30
	v_mul_f32_e32 v40, 0xbfb8aa3b, v31
	v_mul_f32_e32 v41, 0xbfb8aa3b, v24
	v_mul_f32_e32 v42, 0xbfb8aa3b, v25
	v_mul_f32_e32 v43, 0xbfb8aa3b, v26
	v_mul_f32_e32 v44, 0xbfb8aa3b, v27
	v_exp_f32_e32 v33, v33
	v_exp_f32_e32 v38, v38
	v_exp_f32_e32 v39, v39
	v_exp_f32_e32 v40, v40
	v_exp_f32_e32 v41, v41
	v_exp_f32_e32 v42, v42
	v_exp_f32_e32 v43, v43
	v_exp_f32_e32 v44, v44
	v_add_f32_e32 v33, 1.0, v33
	v_add_f32_e32 v45, 1.0, v38
	v_add_f32_e32 v46, 1.0, v39
	v_add_f32_e32 v47, 1.0, v40
	v_add_f32_e32 v48, 1.0, v41
	v_add_f32_e32 v49, 1.0, v42
	v_add_f32_e32 v50, 1.0, v43
	v_add_f32_e32 v51, 1.0, v44
	v_rcp_f32_e32 v38, v33
	v_rcp_f32_e32 v39, v45
	v_rcp_f32_e32 v40, v46
	v_rcp_f32_e32 v41, v47
	v_rcp_f32_e32 v42, v48
	v_rcp_f32_e32 v43, v49
	v_rcp_f32_e32 v44, v50
	v_rcp_f32_e32 v45, v51
	v_lshl_add_u64 v[34:35], v[34:35], 0, s[18:19]
	v_pk_mul_f32 v[28:29], v[28:29], v[38:39]
	v_pk_mul_f32 v[30:31], v[30:31], v[40:41]
	v_pk_mul_f32 v[24:25], v[24:25], v[42:43]
	v_pk_mul_f32 v[26:27], v[26:27], v[44:45]
	v_lshl_add_u64 v[34:35], v[34:35], 0, s[6:7]
	v_pk_mul_f32 v[20:21], v[20:21], v[28:29]
	v_pk_mul_f32 v[22:23], v[22:23], v[30:31]
	v_pk_mul_f32 v[24:25], v[16:17], v[24:25]
	v_pk_mul_f32 v[26:27], v[18:19], v[26:27]
	v_lshl_add_u64 v[34:35], v[34:35], 0, v[136:137]
	v_cvt_pk_bf16_f32 v16, v20, v21
	v_cvt_pk_bf16_f32 v17, v22, v23
	v_cvt_pk_bf16_f32 v18, v24, v25
	v_cvt_pk_bf16_f32 v19, v26, v27
	global_store_dwordx4 v[34:35], v[16:19], off
	s_nop 0
	s_andn2_b64 vcc, exec, s[4:5]
	v_mad_i64_i32 v[16:17], s[0:1], v216, s49, v[146:147]
	v_lshl_add_u64 v[16:17], v[16:17], 0, s[18:19]
	v_lshl_add_u64 v[16:17], v[16:17], 0, s[6:7]
	v_lshl_add_u64 v[16:17], v[16:17], 0, v[136:137]
	s_waitcnt vmcnt(7)
	v_fmamk_f32 v18, v183, 0x3a800000, v158
	v_mul_f32_e32 v19, 0x4b800000, v18
	v_cmp_gt_f32_e64 s[0:1], s50, v18
	s_nop 1
	v_cndmask_b32_e64 v18, v18, v19, s[0:1]
	v_rsq_f32_e32 v18, v18
	s_nop 0
	v_mul_f32_e32 v19, 0x45800000, v18
	v_cndmask_b32_e64 v18, v18, v19, s[0:1]
	v_pk_mul_f32 v[12:13], v[12:13], v[18:19] op_sel_hi:[1,0]
	v_pk_mul_f32 v[14:15], v[14:15], v[18:19] op_sel_hi:[1,0]
	v_pk_mul_f32 v[8:9], v[8:9], v[18:19] op_sel_hi:[1,0]
	v_pk_mul_f32 v[10:11], v[10:11], v[18:19] op_sel_hi:[1,0]
	v_pk_mul_f32 v[4:5], v[4:5], v[18:19] op_sel_hi:[1,0]
	v_pk_mul_f32 v[6:7], v[6:7], v[18:19] op_sel_hi:[1,0]
	v_pk_mul_f32 v[0:1], v[0:1], v[18:19] op_sel_hi:[1,0]
	v_pk_mul_f32 v[2:3], v[2:3], v[18:19] op_sel_hi:[1,0]
	v_mul_f32_e32 v18, 0xbfb8aa3b, v12
	v_mul_f32_e32 v19, 0xbfb8aa3b, v13
	v_mul_f32_e32 v20, 0xbfb8aa3b, v14
	v_mul_f32_e32 v21, 0xbfb8aa3b, v15
	v_mul_f32_e32 v22, 0xbfb8aa3b, v8
	v_mul_f32_e32 v23, 0xbfb8aa3b, v9
	v_mul_f32_e32 v24, 0xbfb8aa3b, v10
	v_mul_f32_e32 v25, 0xbfb8aa3b, v11
	v_exp_f32_e32 v18, v18
	v_exp_f32_e32 v19, v19
	v_exp_f32_e32 v20, v20
	v_exp_f32_e32 v21, v21
	v_exp_f32_e32 v22, v22
	v_exp_f32_e32 v23, v23
	v_exp_f32_e32 v24, v24
	v_exp_f32_e32 v25, v25
	v_add_f32_e32 v18, 1.0, v18
	v_add_f32_e32 v19, 1.0, v19
	v_add_f32_e32 v20, 1.0, v20
	v_add_f32_e32 v21, 1.0, v21
	v_add_f32_e32 v22, 1.0, v22
	v_add_f32_e32 v23, 1.0, v23
	v_add_f32_e32 v24, 1.0, v24
	v_add_f32_e32 v25, 1.0, v25
	v_rcp_f32_e32 v18, v18
	v_rcp_f32_e32 v19, v19
	v_rcp_f32_e32 v20, v20
	v_rcp_f32_e32 v21, v21
	v_rcp_f32_e32 v22, v22
	v_rcp_f32_e32 v23, v23
	v_rcp_f32_e32 v24, v24
	v_rcp_f32_e32 v25, v25
	v_pk_mul_f32 v[12:13], v[12:13], v[18:19]
	v_pk_mul_f32 v[14:15], v[14:15], v[20:21]
	v_pk_mul_f32 v[8:9], v[8:9], v[22:23]
	v_pk_mul_f32 v[10:11], v[10:11], v[24:25]
	v_pk_mul_f32 v[4:5], v[4:5], v[12:13]
	v_pk_mul_f32 v[6:7], v[6:7], v[14:15]
	v_pk_mul_f32 v[8:9], v[0:1], v[8:9]
	v_pk_mul_f32 v[10:11], v[2:3], v[10:11]
	v_cvt_pk_bf16_f32 v0, v4, v5
	v_cvt_pk_bf16_f32 v1, v6, v7
	v_cvt_pk_bf16_f32 v2, v8, v9
	v_cvt_pk_bf16_f32 v3, v10, v11
	s_mov_b64 s[0:1], -1
	global_store_dwordx4 v[16:17], v[0:3], off
	s_cbranch_vccnz .LBB0_2269
	s_andn2_b64 vcc, exec, s[10:11]
	s_cbranch_vccnz .LBB0_2268
	s_barrier
	s_branch .LBB0_2268

; #define LAS __attribute__((address_space(3)))
; #define GSYNC() xcd_barrier(xbar)
; #define RUN_PH(n) RUN_PH1(n) if (DUP == n) { grid.sync(); if (n == 8) { if (blockIdx.x == 0 && tid == 0) ((unsigned*)(p.ws + W_CTR))[0] = 0u; grid.sync(); } RUN_PH1(n) }
; __global__ void __launch_bounds__(512) k_fwd(Prm p) {
;     extern __shared__ __attribute__((aligned(16))) unsigned char lds[];
;     const int tid = threadIdx.x, lane = tid & 63, wid = __builtin_amdgcn_readfirstlane(tid >> 6);
;     cg::grid_group grid = cg::this_grid();
;     volatile LAS unsigned* bst = (volatile LAS unsigned*)((LAS unsigned char*)lds + (LDS_BYTES - 32));
;     if (tid == 0) { bst[0] = 0u; bst[1] = 0u; }
;     __syncthreads();
;     const XcdBarrier xbar = xcd_barrier_post((unsigned*)(p.ws + W_BAR), bst);
;     ...
;     if (p.pad == 0x5eed) grid.sync();
;     RUN_PH(0) GSYNC(); RUN_PH(1) GSYNC(); RUN_PH(2) GSYNC(); RUN_PH(19) GSYNC(); RUN_PH(20) GSYNC(); RUN_PH(4) GSYNC(); RUN_PH(5) GSYNC(); RUN_PH(6) RUN_PH(15) RUN_PH(16) RUN_PH(17) GSYNC(); RUN_PH(7) GSYNC();
;     RUN_PH(8) GSYNC(); RUN_PH(9) GSYNC(); RUN_PH(10) GSYNC(); RUN_PH(12) GSYNC(); RUN_PH(13) GSYNC(); RUN_PH(21) GSYNC(); RUN_PH(22) GSYNC(); RUN_PH(14)
; }
	.amdhsa_kernel _Z5k_fwd3Prm
		.amdhsa_group_segment_fixed_size 0
		.amdhsa_private_segment_fixed_size 0
		.amdhsa_kernarg_size 496
		.amdhsa_user_sgpr_count 2
		.amdhsa_user_sgpr_dispatch_ptr 0
		.amdhsa_user_sgpr_queue_ptr 0
		.amdhsa_user_sgpr_kernarg_segment_ptr 1
		.amdhsa_user_sgpr_dispatch_id 0
		.amdhsa_user_sgpr_kernarg_preload_length 0
		.amdhsa_user_sgpr_kernarg_preload_offset 0
		.amdhsa_user_sgpr_private_segment_size 0
		.amdhsa_uses_dynamic_stack 0
		.amdhsa_enable_private_segment 0
		.amdhsa_system_sgpr_workgroup_id_x 1
		.amdhsa_system_sgpr_workgroup_id_y 0
		.amdhsa_system_sgpr_workgroup_id_z 0
		.amdhsa_system_sgpr_workgroup_info 0
		.amdhsa_system_vgpr_workitem_id 2
		.amdhsa_next_free_vgpr 256
		.amdhsa_next_free_sgpr 98
		.amdhsa_accum_offset 256
		.amdhsa_reserve_vcc 1
		.amdhsa_float_round_mode_32 0
		.amdhsa_float_round_mode_16_64 0
		.amdhsa_float_denorm_mode_32 3
		.amdhsa_float_denorm_mode_16_64 3
		.amdhsa_dx10_clamp 1
		.amdhsa_ieee_mode 1
		.amdhsa_fp16_overflow 0
		.amdhsa_tg_split 0
		.amdhsa_exception_fp_ieee_invalid_op 0
		.amdhsa_exception_fp_denorm_src 0
		.amdhsa_exception_fp_ieee_div_zero 0
		.amdhsa_exception_fp_ieee_overflow 0
		.amdhsa_exception_fp_ieee_underflow 0
		.amdhsa_exception_fp_ieee_inexact 0
		.amdhsa_exception_int_div_zero 0
	.end_amdhsa_kernel

; #define LAS __attribute__((address_space(3)))
; #define GSYNC() xcd_barrier(xbar)
; #define RUN_PH(n) RUN_PH1(n) if (DUP == n) { grid.sync(); if (n == 8) { if (blockIdx.x == 0 && tid == 0) ((unsigned*)(p.ws + W_CTR))[0] = 0u; grid.sync(); } RUN_PH1(n) }
; __global__ void __launch_bounds__(512) k_fwd(Prm p) {
;     extern __shared__ __attribute__((aligned(16))) unsigned char lds[];
;     const int tid = threadIdx.x, lane = tid & 63, wid = __builtin_amdgcn_readfirstlane(tid >> 6);
;     cg::grid_group grid = cg::this_grid();
;     volatile LAS unsigned* bst = (volatile LAS unsigned*)((LAS unsigned char*)lds + (LDS_BYTES - 32));
;     if (tid == 0) { bst[0] = 0u; bst[1] = 0u; }
;     __syncthreads();
;     const XcdBarrier xbar = xcd_barrier_post((unsigned*)(p.ws + W_BAR), bst);
;     ...
;     if (p.pad == 0x5eed) grid.sync();
;     RUN_PH(0) GSYNC(); RUN_PH(1) GSYNC(); RUN_PH(2) GSYNC(); RUN_PH(19) GSYNC(); RUN_PH(20) GSYNC(); RUN_PH(4) GSYNC(); RUN_PH(5) GSYNC(); RUN_PH(6) RUN_PH(15) RUN_PH(16) RUN_PH(17) GSYNC(); RUN_PH(7) GSYNC();
;     RUN_PH(8) GSYNC(); RUN_PH(9) GSYNC(); RUN_PH(10) GSYNC(); RUN_PH(12) GSYNC(); RUN_PH(13) GSYNC(); RUN_PH(21) GSYNC(); RUN_PH(22) GSYNC(); RUN_PH(14)
; }
amdhsa.kernels:
  - .agpr_count:     0
    .args:
      - .offset:         0
        .size:           240
        .value_kind:     by_value
      - .offset:         240
        .size:           4
        .value_kind:     hidden_block_count_x
      - .offset:         244
        .size:           4
        .value_kind:     hidden_block_count_y
      - .offset:         248
        .size:           4
        .value_kind:     hidden_block_count_z
      - .offset:         252
        .size:           2
        .value_kind:     hidden_group_size_x
      - .offset:         254
        .size:           2
        .value_kind:     hidden_group_size_y
      - .offset:         256
        .size:           2
        .value_kind:     hidden_group_size_z
      - .offset:         258
        .size:           2
        .value_kind:     hidden_remainder_x
      - .offset:         260
        .size:           2
        .value_kind:     hidden_remainder_y
      - .offset:         262
        .size:           2
        .value_kind:     hidden_remainder_z
      - .offset:         280
        .size:           8
        .value_kind:     hidden_global_offset_x
      - .offset:         288
        .size:           8
        .value_kind:     hidden_global_offset_y
      - .offset:         296
        .size:           8
        .value_kind:     hidden_global_offset_z
      - .offset:         304
        .size:           2
        .value_kind:     hidden_grid_dims
      - .offset:         328
        .size:           8
        .value_kind:     hidden_multigrid_sync_arg
      - .offset:         360
        .size:           4
        .value_kind:     hidden_dynamic_lds_size
    .group_segment_fixed_size: 0
    .kernarg_segment_align: 8
    .kernarg_segment_size: 496
    .language:       OpenCL C
    .language_version:
      - 2
      - 0
    .max_flat_workgroup_size: 512
    .name:           _Z5k_fwd3Prm
    .private_segment_fixed_size: 0
    .sgpr_count:     104
    .sgpr_spill_count: 153
    .symbol:         _Z5k_fwd3Prm.kd
    .uniform_work_group_size: 1
    .uses_dynamic_stack: false
    .vgpr_count:     256
    .vgpr_spill_count: 0
    .wavefront_size: 64
